# conv rows stored plain again (kept in L2 for the output projection), weights still write-through
# speedup vs baseline: 1.0008x; 1.0008x over previous
; __device__ __forceinline__ unsigned cvt_pk_bf16(float lo, float hi) { unsigned r; asm volatile("v_cvt_pk_bf16_f32 %0, %1, %2" : "=v"(r) : "v"(lo), "v"(hi)); return r; }
; __device__ __forceinline__ float bf_lo(unsigned w) { return __uint_as_float(w << 16); }
; __device__ __forceinline__ float bf_hi(unsigned w) { return __uint_as_float(w & 0xffff0000u); }
; __global__ void __launch_bounds__(512, 2) trunk_fwd(Args args) {
;     ...
;                 for (int rr = 0; rr < 16; ++rr) {
;                     const int r = r0 + rr;
;                     const u32x4 gb = gb_n, gu = gu_n; const f32x4 pv4 = pv_n;
;                     if (rr < 15) { gb_n = *(const u32x4*)(Z + (size_t)(r + 1) * INP + 768 + c0); gu_n = *(const u32x4*)(Z + (size_t)(r + 1) * INP + 1280 + c0);
;                                    pv_n = *(const f32x4*)(pl + (size_t)(r + 1) * PLE + lane * 4); }
;                     float cv[8], uu[8]; float ss = 0.f;
; #pragma unroll
;                     for (int i = 0; i < 4; ++i) {
;                         uu[2 * i] = bf_lo(gu[i]); uu[2 * i + 1] = bf_hi(gu[i]);
;                         cv[2 * i] = bf_lo(gb[i]) * (w0[2 * i] * uu[2 * i] + w1[2 * i] * u1[2 * i] + w2[2 * i] * u2[2 * i]);
;                         cv[2 * i + 1] = bf_hi(gb[i]) * (w0[2 * i + 1] * uu[2 * i + 1] + w1[2 * i + 1] * u1[2 * i + 1] + w2[2 * i + 1] * u2[2 * i + 1]);
;                     }
; #pragma unroll
;                     for (int i = 0; i < 8; ++i) { ss += cv[i] * cv[i]; u2[i] = u1[i]; u1[i] = uu[i]; }
;                     ss = wave_sum(ss);
;                     const float rc = rsqrtf(ss * (1.0f / 512.0f) + EPS);
;                     u32x4 oc;
; #pragma unroll
;                     for (int i = 0; i < 4; ++i) oc[i] = cvt_pk_bf16(cv[2 * i] * rc, cv[2 * i + 1] * rc);
;                     *(u32x4*)(MIX + (size_t)r * 1024 + 512 + c0) = oc;
.Lcv_taps_ok:
	v_mad_i64_i32 v[152:153], vcc, s41, v221, v[58:59]
	s_add_u32 s41, s41, 1
	global_load_dwordx4 v[2:5], v[152:153], off offset:1536 nt
	global_load_dwordx4 v[18:21], v[152:153], off offset:2560 nt
	v_mad_i64_i32 v[152:153], vcc, s41, v221, v[58:59]
	s_add_u32 s41, s41, 1
	global_load_dwordx4 v[6:9], v[152:153], off offset:1536 nt
	global_load_dwordx4 v[22:25], v[152:153], off offset:2560 nt
	v_mad_i64_i32 v[152:153], vcc, s41, v221, v[58:59]
	s_add_u32 s41, s41, 1
	global_load_dwordx4 v[10:13], v[152:153], off offset:1536 nt
	global_load_dwordx4 v[26:29], v[152:153], off offset:2560 nt
	v_mad_i64_i32 v[152:153], vcc, s41, v221, v[58:59]
	s_add_u32 s41, s41, 1
	global_load_dwordx4 v[14:17], v[152:153], off offset:1536 nt
	global_load_dwordx4 v[30:33], v[152:153], off offset:2560 nt
	s_waitcnt vmcnt(6)
	v_lshlrev_b32_e32 v188, 16, v18
	v_and_b32_e32 v189, 0xffff0000, v18
	v_lshlrev_b32_e32 v190, 16, v19
	v_and_b32_e32 v191, 0xffff0000, v19
	v_lshlrev_b32_e32 v192, 16, v20
	v_and_b32_e32 v193, 0xffff0000, v20
	v_lshlrev_b32_e32 v194, 16, v21
	v_and_b32_e32 v195, 0xffff0000, v21
	v_mul_f32_e32 v140, v164, v188
	v_mul_f32_e32 v141, v165, v189
	v_mul_f32_e32 v142, v166, v190
	v_mul_f32_e32 v143, v167, v191
	v_mul_f32_e32 v144, v168, v192
	v_mul_f32_e32 v145, v169, v193
	v_mul_f32_e32 v146, v170, v194
	v_mul_f32_e32 v147, v171, v195
	v_fmac_f32_e32 v140, v172, v204
	v_fmac_f32_e32 v141, v173, v205
	v_fmac_f32_e32 v142, v174, v206
	v_fmac_f32_e32 v143, v175, v207
	v_fmac_f32_e32 v144, v176, v208
	v_fmac_f32_e32 v145, v177, v209
	v_fmac_f32_e32 v146, v178, v210
	v_fmac_f32_e32 v147, v179, v211
	v_fmac_f32_e32 v140, v180, v196
	v_fmac_f32_e32 v141, v181, v197
	v_fmac_f32_e32 v142, v182, v198
	v_fmac_f32_e32 v143, v183, v199
	v_fmac_f32_e32 v144, v184, v200
	v_fmac_f32_e32 v145, v185, v201
	v_fmac_f32_e32 v146, v186, v202
	v_fmac_f32_e32 v147, v187, v203
	v_lshlrev_b32_e32 v150, 16, v2
	v_and_b32_e32 v151, 0xffff0000, v2
	v_mul_f32_e32 v140, v150, v140
	v_mul_f32_e32 v141, v151, v141
	v_lshlrev_b32_e32 v150, 16, v3
	v_and_b32_e32 v151, 0xffff0000, v3
	v_mul_f32_e32 v142, v150, v142
	v_mul_f32_e32 v143, v151, v143
	v_lshlrev_b32_e32 v150, 16, v4
	v_and_b32_e32 v151, 0xffff0000, v4
	v_mul_f32_e32 v144, v150, v144
	v_mul_f32_e32 v145, v151, v145
	v_lshlrev_b32_e32 v150, 16, v5
	v_and_b32_e32 v151, 0xffff0000, v5
	v_mul_f32_e32 v146, v150, v146
	v_mul_f32_e32 v147, v151, v147
	v_mul_f32_e32 v148, v140, v140
	v_fmac_f32_e32 v148, v141, v141
	v_fmac_f32_e32 v148, v142, v142
	v_fmac_f32_e32 v148, v143, v143
	v_fmac_f32_e32 v148, v144, v144
	v_fmac_f32_e32 v148, v145, v145
	v_fmac_f32_e32 v148, v146, v146
	v_fmac_f32_e32 v148, v147, v147
	v_mad_i64_i32 v[152:153], vcc, s41, v221, v[58:59]
	s_add_u32 s41, s41, 1
	global_load_dwordx4 v[2:5], v[152:153], off offset:1536 nt
	global_load_dwordx4 v[18:21], v[152:153], off offset:2560 nt
	s_nop 1
	v_add_f32_dpp v148, v148, v148 quad_perm:[1,0,3,2] row_mask:0xf bank_mask:0xf
	s_nop 1
	v_add_f32_dpp v148, v148, v148 quad_perm:[2,3,0,1] row_mask:0xf bank_mask:0xf
	s_nop 1
	v_add_f32_dpp v148, v148, v148 row_half_mirror row_mask:0xf bank_mask:0xf
	s_nop 1
	v_add_f32_dpp v148, v148, v148 row_mirror row_mask:0xf bank_mask:0xf
	s_nop 1
	v_add_f32_dpp v148, v148, v148 row_bcast:15 row_mask:0xa bank_mask:0xf
	s_nop 1
	v_add_f32_dpp v148, v148, v148 row_bcast:31 row_mask:0xc bank_mask:0xf
	s_nop 0
	v_readlane_b32 s0, v148, 63
	s_nop 1
	v_mov_b32_e32 v148, s0
	v_fmamk_f32 v148, v148, 0x3b000000, v162
	v_mul_f32_e32 v150, 0x4b800000, v148
	v_cmp_gt_f32_e32 vcc, s31, v148
	s_nop 1
	v_cndmask_b32_e32 v148, v148, v150, vcc
	v_rsq_f32_e32 v148, v148
	s_nop 0
	v_mul_f32_e32 v150, 0x45800000, v148
	v_cndmask_b32_e32 v149, v148, v150, vcc
	v_mul_f32_e32 v140, v149, v140
	v_mul_f32_e32 v141, v149, v141
	v_mul_f32_e32 v142, v149, v142
	v_mul_f32_e32 v143, v149, v143
	v_mul_f32_e32 v144, v149, v144
	v_mul_f32_e32 v145, v149, v145
	v_mul_f32_e32 v146, v149, v146
	v_mul_f32_e32 v147, v149, v147
	v_cvt_pk_bf16_f32 v140, v140, v141
	v_cvt_pk_bf16_f32 v141, v142, v143
	v_cvt_pk_bf16_f32 v142, v144, v145
	v_cvt_pk_bf16_f32 v143, v146, v147
	global_store_dwordx4 v[156:157], v[140:143], off
	s_waitcnt vmcnt(7)
	v_lshlrev_b32_e32 v196, 16, v22
	v_and_b32_e32 v197, 0xffff0000, v22
	v_lshlrev_b32_e32 v198, 16, v23
	v_and_b32_e32 v199, 0xffff0000, v23
	v_lshlrev_b32_e32 v200, 16, v24
	v_and_b32_e32 v201, 0xffff0000, v24
	v_lshlrev_b32_e32 v202, 16, v25
	v_and_b32_e32 v203, 0xffff0000, v25
	v_mul_f32_e32 v140, v164, v196
	v_mul_f32_e32 v141, v165, v197
	v_mul_f32_e32 v142, v166, v198
	v_mul_f32_e32 v143, v167, v199
	v_mul_f32_e32 v144, v168, v200
	v_mul_f32_e32 v145, v169, v201
	v_mul_f32_e32 v146, v170, v202
	v_mul_f32_e32 v147, v171, v203
	v_fmac_f32_e32 v140, v172, v188
	v_fmac_f32_e32 v141, v173, v189
	v_fmac_f32_e32 v142, v174, v190
	v_fmac_f32_e32 v143, v175, v191
	v_fmac_f32_e32 v144, v176, v192
	v_fmac_f32_e32 v145, v177, v193
	v_fmac_f32_e32 v146, v178, v194
	v_fmac_f32_e32 v147, v179, v195
	v_fmac_f32_e32 v140, v180, v204
	v_fmac_f32_e32 v141, v181, v205
	v_fmac_f32_e32 v142, v182, v206
	v_fmac_f32_e32 v143, v183, v207
	v_fmac_f32_e32 v144, v184, v208
	v_fmac_f32_e32 v145, v185, v209
	v_fmac_f32_e32 v146, v186, v210
	v_fmac_f32_e32 v147, v187, v211
	v_lshlrev_b32_e32 v150, 16, v6
	v_and_b32_e32 v151, 0xffff0000, v6
	v_mul_f32_e32 v140, v150, v140
	v_mul_f32_e32 v141, v151, v141
	v_lshlrev_b32_e32 v150, 16, v7
	v_and_b32_e32 v151, 0xffff0000, v7
	v_mul_f32_e32 v142, v150, v142
	v_mul_f32_e32 v143, v151, v143
	v_lshlrev_b32_e32 v150, 16, v8
	v_and_b32_e32 v151, 0xffff0000, v8
	v_mul_f32_e32 v144, v150, v144
; __device__ __forceinline__ unsigned cvt_pk_bf16(float lo, float hi) { unsigned r; asm volatile("v_cvt_pk_bf16_f32 %0, %1, %2" : "=v"(r) : "v"(lo), "v"(hi)); return r; }
; __device__ __forceinline__ float bf_lo(unsigned w) { return __uint_as_float(w << 16); }
; __device__ __forceinline__ float bf_hi(unsigned w) { return __uint_as_float(w & 0xffff0000u); }
; __global__ void __launch_bounds__(512, 2) trunk_fwd(Args args) {
;     ...
;                 for (int rr = 0; rr < 16; ++rr) {
;                     const int r = r0 + rr;
;                     const u32x4 gb = gb_n, gu = gu_n; const f32x4 pv4 = pv_n;
;                     if (rr < 15) { gb_n = *(const u32x4*)(Z + (size_t)(r + 1) * INP + 768 + c0); gu_n = *(const u32x4*)(Z + (size_t)(r + 1) * INP + 1280 + c0);
;                                    pv_n = *(const f32x4*)(pl + (size_t)(r + 1) * PLE + lane * 4); }
;                     float cv[8], uu[8]; float ss = 0.f;
; #pragma unroll
;                     for (int i = 0; i < 4; ++i) {
;                         uu[2 * i] = bf_lo(gu[i]); uu[2 * i + 1] = bf_hi(gu[i]);
;                         cv[2 * i] = bf_lo(gb[i]) * (w0[2 * i] * uu[2 * i] + w1[2 * i] * u1[2 * i] + w2[2 * i] * u2[2 * i]);
;                         cv[2 * i + 1] = bf_hi(gb[i]) * (w0[2 * i + 1] * uu[2 * i + 1] + w1[2 * i + 1] * u1[2 * i + 1] + w2[2 * i + 1] * u2[2 * i + 1]);
;                     }
; #pragma unroll
;                     for (int i = 0; i < 8; ++i) { ss += cv[i] * cv[i]; u2[i] = u1[i]; u1[i] = uu[i]; }
;                     ss = wave_sum(ss);
;                     const float rc = rsqrtf(ss * (1.0f / 512.0f) + EPS);
;                     u32x4 oc;
; #pragma unroll
;                     for (int i = 0; i < 4; ++i) oc[i] = cvt_pk_bf16(cv[2 * i] * rc, cv[2 * i + 1] * rc);
;                     *(u32x4*)(MIX + (size_t)r * 1024 + 512 + c0) = oc;
	v_mul_f32_e32 v145, v151, v145
	v_lshlrev_b32_e32 v150, 16, v9
	v_and_b32_e32 v151, 0xffff0000, v9
	v_mul_f32_e32 v146, v150, v146
	v_mul_f32_e32 v147, v151, v147
	v_mul_f32_e32 v148, v140, v140
	v_fmac_f32_e32 v148, v141, v141
	v_fmac_f32_e32 v148, v142, v142
	v_fmac_f32_e32 v148, v143, v143
	v_fmac_f32_e32 v148, v144, v144
	v_fmac_f32_e32 v148, v145, v145
	v_fmac_f32_e32 v148, v146, v146
	v_fmac_f32_e32 v148, v147, v147
	v_mad_i64_i32 v[152:153], vcc, s41, v221, v[58:59]
	s_add_u32 s41, s41, 1
	global_load_dwordx4 v[6:9], v[152:153], off offset:1536 nt
	global_load_dwordx4 v[22:25], v[152:153], off offset:2560 nt
	s_nop 1
	v_add_f32_dpp v148, v148, v148 quad_perm:[1,0,3,2] row_mask:0xf bank_mask:0xf
	s_nop 1
	v_add_f32_dpp v148, v148, v148 quad_perm:[2,3,0,1] row_mask:0xf bank_mask:0xf
	s_nop 1
	v_add_f32_dpp v148, v148, v148 row_half_mirror row_mask:0xf bank_mask:0xf
	s_nop 1
	v_add_f32_dpp v148, v148, v148 row_mirror row_mask:0xf bank_mask:0xf
	s_nop 1
	v_add_f32_dpp v148, v148, v148 row_bcast:15 row_mask:0xa bank_mask:0xf
	s_nop 1
	v_add_f32_dpp v148, v148, v148 row_bcast:31 row_mask:0xc bank_mask:0xf
	s_nop 0
	v_readlane_b32 s0, v148, 63
	s_nop 1
	v_mov_b32_e32 v148, s0
	v_fmamk_f32 v148, v148, 0x3b000000, v162
	v_mul_f32_e32 v150, 0x4b800000, v148
	v_cmp_gt_f32_e32 vcc, s31, v148
	s_nop 1
	v_cndmask_b32_e32 v148, v148, v150, vcc
	v_rsq_f32_e32 v148, v148
	s_nop 0
	v_mul_f32_e32 v150, 0x45800000, v148
	v_cndmask_b32_e32 v149, v148, v150, vcc
	v_mul_f32_e32 v140, v149, v140
	v_mul_f32_e32 v141, v149, v141
	v_mul_f32_e32 v142, v149, v142
	v_mul_f32_e32 v143, v149, v143
	v_mul_f32_e32 v144, v149, v144
	v_mul_f32_e32 v145, v149, v145
	v_mul_f32_e32 v146, v149, v146
	v_mul_f32_e32 v147, v149, v147
	v_cvt_pk_bf16_f32 v140, v140, v141
	v_cvt_pk_bf16_f32 v141, v142, v143
	v_cvt_pk_bf16_f32 v142, v144, v145
	v_cvt_pk_bf16_f32 v143, v146, v147
	global_store_dwordx4 v[156:157], v[140:143], off offset:2048
	v_lshl_add_u64 v[156:157], v[156:157], 0, s[20:21]
	s_waitcnt vmcnt(8)
	v_lshlrev_b32_e32 v204, 16, v26
	v_and_b32_e32 v205, 0xffff0000, v26
	v_lshlrev_b32_e32 v206, 16, v27
	v_and_b32_e32 v207, 0xffff0000, v27
	v_lshlrev_b32_e32 v208, 16, v28
	v_and_b32_e32 v209, 0xffff0000, v28
	v_lshlrev_b32_e32 v210, 16, v29
	v_and_b32_e32 v211, 0xffff0000, v29
	v_mul_f32_e32 v140, v164, v204
	v_mul_f32_e32 v141, v165, v205
	v_mul_f32_e32 v142, v166, v206
	v_mul_f32_e32 v143, v167, v207
	v_mul_f32_e32 v144, v168, v208
	v_mul_f32_e32 v145, v169, v209
	v_mul_f32_e32 v146, v170, v210
	v_mul_f32_e32 v147, v171, v211
	v_fmac_f32_e32 v140, v172, v196
	v_fmac_f32_e32 v141, v173, v197
	v_fmac_f32_e32 v142, v174, v198
	v_fmac_f32_e32 v143, v175, v199
	v_fmac_f32_e32 v144, v176, v200
	v_fmac_f32_e32 v145, v177, v201
	v_fmac_f32_e32 v146, v178, v202
	v_fmac_f32_e32 v147, v179, v203
	v_fmac_f32_e32 v140, v180, v188
	v_fmac_f32_e32 v141, v181, v189
	v_fmac_f32_e32 v142, v182, v190
	v_fmac_f32_e32 v143, v183, v191
	v_fmac_f32_e32 v144, v184, v192
	v_fmac_f32_e32 v145, v185, v193
	v_fmac_f32_e32 v146, v186, v194
	v_fmac_f32_e32 v147, v187, v195
	v_lshlrev_b32_e32 v150, 16, v10
	v_and_b32_e32 v151, 0xffff0000, v10
	v_mul_f32_e32 v140, v150, v140
	v_mul_f32_e32 v141, v151, v141
	v_lshlrev_b32_e32 v150, 16, v11
	v_and_b32_e32 v151, 0xffff0000, v11
	v_mul_f32_e32 v142, v150, v142
	v_mul_f32_e32 v143, v151, v143
	v_lshlrev_b32_e32 v150, 16, v12
	v_and_b32_e32 v151, 0xffff0000, v12
	v_mul_f32_e32 v144, v150, v144
	v_mul_f32_e32 v145, v151, v145
	v_lshlrev_b32_e32 v150, 16, v13
	v_and_b32_e32 v151, 0xffff0000, v13
	v_mul_f32_e32 v146, v150, v146
	v_mul_f32_e32 v147, v151, v147
	v_mul_f32_e32 v148, v140, v140
	v_fmac_f32_e32 v148, v141, v141
	v_fmac_f32_e32 v148, v142, v142
	v_fmac_f32_e32 v148, v143, v143
	v_fmac_f32_e32 v148, v144, v144
	v_fmac_f32_e32 v148, v145, v145
	v_fmac_f32_e32 v148, v146, v146
	v_fmac_f32_e32 v148, v147, v147
	v_mad_i64_i32 v[152:153], vcc, s41, v221, v[58:59]
	s_add_u32 s41, s41, 1
	global_load_dwordx4 v[10:13], v[152:153], off offset:1536 nt
	global_load_dwordx4 v[26:29], v[152:153], off offset:2560 nt
	s_nop 1
	v_add_f32_dpp v148, v148, v148 quad_perm:[1,0,3,2] row_mask:0xf bank_mask:0xf
	s_nop 1
	v_add_f32_dpp v148, v148, v148 quad_perm:[2,3,0,1] row_mask:0xf bank_mask:0xf
	s_nop 1
	v_add_f32_dpp v148, v148, v148 row_half_mirror row_mask:0xf bank_mask:0xf
	s_nop 1
	v_add_f32_dpp v148, v148, v148 row_mirror row_mask:0xf bank_mask:0xf
	s_nop 1
	v_add_f32_dpp v148, v148, v148 row_bcast:15 row_mask:0xa bank_mask:0xf
	s_nop 1
	v_add_f32_dpp v148, v148, v148 row_bcast:31 row_mask:0xc bank_mask:0xf
	s_nop 0
	v_readlane_b32 s0, v148, 63
	s_nop 1
	v_mov_b32_e32 v148, s0
	v_fmamk_f32 v148, v148, 0x3b000000, v162
	v_mul_f32_e32 v150, 0x4b800000, v148
	v_cmp_gt_f32_e32 vcc, s31, v148
	s_nop 1
	v_cndmask_b32_e32 v148, v148, v150, vcc
	v_rsq_f32_e32 v148, v148
	s_nop 0
	v_mul_f32_e32 v150, 0x45800000, v148
	v_cndmask_b32_e32 v149, v148, v150, vcc
	v_mul_f32_e32 v140, v149, v140
	v_mul_f32_e32 v141, v149, v141
	v_mul_f32_e32 v142, v149, v142
	v_mul_f32_e32 v143, v149, v143
	v_mul_f32_e32 v144, v149, v144
	v_mul_f32_e32 v145, v149, v145
	v_mul_f32_e32 v146, v149, v146
	v_mul_f32_e32 v147, v149, v147
	v_cvt_pk_bf16_f32 v140, v140, v141
	v_cvt_pk_bf16_f32 v141, v142, v143
	v_cvt_pk_bf16_f32 v142, v144, v145
	v_cvt_pk_bf16_f32 v143, v146, v147
	global_store_dwordx4 v[156:157], v[140:143], off
	s_waitcnt vmcnt(9)
; __device__ __forceinline__ unsigned cvt_pk_bf16(float lo, float hi) { unsigned r; asm volatile("v_cvt_pk_bf16_f32 %0, %1, %2" : "=v"(r) : "v"(lo), "v"(hi)); return r; }
; __device__ __forceinline__ float bf_lo(unsigned w) { return __uint_as_float(w << 16); }
; __device__ __forceinline__ float bf_hi(unsigned w) { return __uint_as_float(w & 0xffff0000u); }
; __global__ void __launch_bounds__(512, 2) trunk_fwd(Args args) {
;     ...
;                 for (int rr = 0; rr < 16; ++rr) {
;                     const int r = r0 + rr;
;                     const u32x4 gb = gb_n, gu = gu_n; const f32x4 pv4 = pv_n;
;                     if (rr < 15) { gb_n = *(const u32x4*)(Z + (size_t)(r + 1) * INP + 768 + c0); gu_n = *(const u32x4*)(Z + (size_t)(r + 1) * INP + 1280 + c0);
;                                    pv_n = *(const f32x4*)(pl + (size_t)(r + 1) * PLE + lane * 4); }
;                     float cv[8], uu[8]; float ss = 0.f;
; #pragma unroll
;                     for (int i = 0; i < 4; ++i) {
;                         uu[2 * i] = bf_lo(gu[i]); uu[2 * i + 1] = bf_hi(gu[i]);
;                         cv[2 * i] = bf_lo(gb[i]) * (w0[2 * i] * uu[2 * i] + w1[2 * i] * u1[2 * i] + w2[2 * i] * u2[2 * i]);
;                         cv[2 * i + 1] = bf_hi(gb[i]) * (w0[2 * i + 1] * uu[2 * i + 1] + w1[2 * i + 1] * u1[2 * i + 1] + w2[2 * i + 1] * u2[2 * i + 1]);
;                     }
; #pragma unroll
;                     for (int i = 0; i < 8; ++i) { ss += cv[i] * cv[i]; u2[i] = u1[i]; u1[i] = uu[i]; }
;                     ss = wave_sum(ss);
;                     const float rc = rsqrtf(ss * (1.0f / 512.0f) + EPS);
;                     u32x4 oc;
; #pragma unroll
;                     for (int i = 0; i < 4; ++i) oc[i] = cvt_pk_bf16(cv[2 * i] * rc, cv[2 * i + 1] * rc);
;                     *(u32x4*)(MIX + (size_t)r * 1024 + 512 + c0) = oc;
	v_lshlrev_b32_e32 v188, 16, v30
	v_and_b32_e32 v189, 0xffff0000, v30
	v_lshlrev_b32_e32 v190, 16, v31
	v_and_b32_e32 v191, 0xffff0000, v31
	v_lshlrev_b32_e32 v192, 16, v32
	v_and_b32_e32 v193, 0xffff0000, v32
	v_lshlrev_b32_e32 v194, 16, v33
	v_and_b32_e32 v195, 0xffff0000, v33
	v_mul_f32_e32 v140, v164, v188
	v_mul_f32_e32 v141, v165, v189
	v_mul_f32_e32 v142, v166, v190
	v_mul_f32_e32 v143, v167, v191
	v_mul_f32_e32 v144, v168, v192
	v_mul_f32_e32 v145, v169, v193
	v_mul_f32_e32 v146, v170, v194
	v_mul_f32_e32 v147, v171, v195
	v_fmac_f32_e32 v140, v172, v204
	v_fmac_f32_e32 v141, v173, v205
	v_fmac_f32_e32 v142, v174, v206
	v_fmac_f32_e32 v143, v175, v207
	v_fmac_f32_e32 v144, v176, v208
	v_fmac_f32_e32 v145, v177, v209
	v_fmac_f32_e32 v146, v178, v210
	v_fmac_f32_e32 v147, v179, v211
	v_fmac_f32_e32 v140, v180, v196
	v_fmac_f32_e32 v141, v181, v197
	v_fmac_f32_e32 v142, v182, v198
	v_fmac_f32_e32 v143, v183, v199
	v_fmac_f32_e32 v144, v184, v200
	v_fmac_f32_e32 v145, v185, v201
	v_fmac_f32_e32 v146, v186, v202
	v_fmac_f32_e32 v147, v187, v203
	v_lshlrev_b32_e32 v150, 16, v14
	v_and_b32_e32 v151, 0xffff0000, v14
	v_mul_f32_e32 v140, v150, v140
	v_mul_f32_e32 v141, v151, v141
	v_lshlrev_b32_e32 v150, 16, v15
	v_and_b32_e32 v151, 0xffff0000, v15
	v_mul_f32_e32 v142, v150, v142
	v_mul_f32_e32 v143, v151, v143
	v_lshlrev_b32_e32 v150, 16, v16
	v_and_b32_e32 v151, 0xffff0000, v16
	v_mul_f32_e32 v144, v150, v144
	v_mul_f32_e32 v145, v151, v145
	v_lshlrev_b32_e32 v150, 16, v17
	v_and_b32_e32 v151, 0xffff0000, v17
	v_mul_f32_e32 v146, v150, v146
	v_mul_f32_e32 v147, v151, v147
	v_mul_f32_e32 v148, v140, v140
	v_fmac_f32_e32 v148, v141, v141
	v_fmac_f32_e32 v148, v142, v142
	v_fmac_f32_e32 v148, v143, v143
	v_fmac_f32_e32 v148, v144, v144
	v_fmac_f32_e32 v148, v145, v145
	v_fmac_f32_e32 v148, v146, v146
	v_fmac_f32_e32 v148, v147, v147
	v_mad_i64_i32 v[152:153], vcc, s41, v221, v[58:59]
	s_add_u32 s41, s41, 1
	global_load_dwordx4 v[14:17], v[152:153], off offset:1536 nt
	global_load_dwordx4 v[30:33], v[152:153], off offset:2560 nt
	s_nop 1
	v_add_f32_dpp v148, v148, v148 quad_perm:[1,0,3,2] row_mask:0xf bank_mask:0xf
	s_nop 1
	v_add_f32_dpp v148, v148, v148 quad_perm:[2,3,0,1] row_mask:0xf bank_mask:0xf
	s_nop 1
	v_add_f32_dpp v148, v148, v148 row_half_mirror row_mask:0xf bank_mask:0xf
	s_nop 1
	v_add_f32_dpp v148, v148, v148 row_mirror row_mask:0xf bank_mask:0xf
	s_nop 1
	v_add_f32_dpp v148, v148, v148 row_bcast:15 row_mask:0xa bank_mask:0xf
	s_nop 1
	v_add_f32_dpp v148, v148, v148 row_bcast:31 row_mask:0xc bank_mask:0xf
	s_nop 0
	v_readlane_b32 s0, v148, 63
	s_nop 1
	v_mov_b32_e32 v148, s0
	v_fmamk_f32 v148, v148, 0x3b000000, v162
	v_mul_f32_e32 v150, 0x4b800000, v148
	v_cmp_gt_f32_e32 vcc, s31, v148
	s_nop 1
	v_cndmask_b32_e32 v148, v148, v150, vcc
	v_rsq_f32_e32 v148, v148
	s_nop 0
	v_mul_f32_e32 v150, 0x45800000, v148
	v_cndmask_b32_e32 v149, v148, v150, vcc
	v_mul_f32_e32 v140, v149, v140
	v_mul_f32_e32 v141, v149, v141
	v_mul_f32_e32 v142, v149, v142
	v_mul_f32_e32 v143, v149, v143
	v_mul_f32_e32 v144, v149, v144
	v_mul_f32_e32 v145, v149, v145
	v_mul_f32_e32 v146, v149, v146
	v_mul_f32_e32 v147, v149, v147
	v_cvt_pk_bf16_f32 v140, v140, v141
	v_cvt_pk_bf16_f32 v141, v142, v143
	v_cvt_pk_bf16_f32 v142, v144, v145
	v_cvt_pk_bf16_f32 v143, v146, v147
	global_store_dwordx4 v[156:157], v[140:143], off offset:2048
	v_lshl_add_u64 v[156:157], v[156:157], 0, s[20:21]
	s_waitcnt vmcnt(10)
	v_lshlrev_b32_e32 v196, 16, v18
	v_and_b32_e32 v197, 0xffff0000, v18
	v_lshlrev_b32_e32 v198, 16, v19
	v_and_b32_e32 v199, 0xffff0000, v19
	v_lshlrev_b32_e32 v200, 16, v20
	v_and_b32_e32 v201, 0xffff0000, v20
	v_lshlrev_b32_e32 v202, 16, v21
	v_and_b32_e32 v203, 0xffff0000, v21
	v_mul_f32_e32 v140, v164, v196
	v_mul_f32_e32 v141, v165, v197
	v_mul_f32_e32 v142, v166, v198
	v_mul_f32_e32 v143, v167, v199
	v_mul_f32_e32 v144, v168, v200
	v_mul_f32_e32 v145, v169, v201
	v_mul_f32_e32 v146, v170, v202
	v_mul_f32_e32 v147, v171, v203
	v_fmac_f32_e32 v140, v172, v188
	v_fmac_f32_e32 v141, v173, v189
	v_fmac_f32_e32 v142, v174, v190
	v_fmac_f32_e32 v143, v175, v191
	v_fmac_f32_e32 v144, v176, v192
	v_fmac_f32_e32 v145, v177, v193
	v_fmac_f32_e32 v146, v178, v194
	v_fmac_f32_e32 v147, v179, v195
	v_fmac_f32_e32 v140, v180, v204
	v_fmac_f32_e32 v141, v181, v205
	v_fmac_f32_e32 v142, v182, v206
	v_fmac_f32_e32 v143, v183, v207
	v_fmac_f32_e32 v144, v184, v208
	v_fmac_f32_e32 v145, v185, v209
	v_fmac_f32_e32 v146, v186, v210
	v_fmac_f32_e32 v147, v187, v211
	v_lshlrev_b32_e32 v150, 16, v2
	v_and_b32_e32 v151, 0xffff0000, v2
	v_mul_f32_e32 v140, v150, v140
	v_mul_f32_e32 v141, v151, v141
	v_lshlrev_b32_e32 v150, 16, v3
	v_and_b32_e32 v151, 0xffff0000, v3
	v_mul_f32_e32 v142, v150, v142
	v_mul_f32_e32 v143, v151, v143
	v_lshlrev_b32_e32 v150, 16, v4
	v_and_b32_e32 v151, 0xffff0000, v4
	v_mul_f32_e32 v144, v150, v144
	v_mul_f32_e32 v145, v151, v145
	v_lshlrev_b32_e32 v150, 16, v5
	v_and_b32_e32 v151, 0xffff0000, v5
	v_mul_f32_e32 v146, v150, v146
	v_mul_f32_e32 v147, v151, v147
	v_mul_f32_e32 v148, v140, v140
	v_fmac_f32_e32 v148, v141, v141
	v_fmac_f32_e32 v148, v142, v142
	v_fmac_f32_e32 v148, v143, v143
	v_fmac_f32_e32 v148, v144, v144
	v_fmac_f32_e32 v148, v145, v145
	v_fmac_f32_e32 v148, v146, v146
	v_fmac_f32_e32 v148, v147, v147
	v_mad_i64_i32 v[152:153], vcc, s41, v221, v[58:59]
	s_add_u32 s41, s41, 1
	global_load_dwordx4 v[2:5], v[152:153], off offset:1536 nt
	global_load_dwordx4 v[18:21], v[152:153], off offset:2560 nt
	s_nop 1
	v_add_f32_dpp v148, v148, v148 quad_perm:[1,0,3,2] row_mask:0xf bank_mask:0xf
	s_nop 1
	v_add_f32_dpp v148, v148, v148 quad_perm:[2,3,0,1] row_mask:0xf bank_mask:0xf
	s_nop 1
	v_add_f32_dpp v148, v148, v148 row_half_mirror row_mask:0xf bank_mask:0xf
	s_nop 1
	v_add_f32_dpp v148, v148, v148 row_mirror row_mask:0xf bank_mask:0xf
	s_nop 1
	v_add_f32_dpp v148, v148, v148 row_bcast:15 row_mask:0xa bank_mask:0xf
	s_nop 1
	v_add_f32_dpp v148, v148, v148 row_bcast:31 row_mask:0xc bank_mask:0xf
	s_nop 0
	v_readlane_b32 s0, v148, 63
	s_nop 1
	v_mov_b32_e32 v148, s0
	v_fmamk_f32 v148, v148, 0x3b000000, v162
	v_mul_f32_e32 v150, 0x4b800000, v148
	v_cmp_gt_f32_e32 vcc, s31, v148
	s_nop 1
	v_cndmask_b32_e32 v148, v148, v150, vcc
	v_rsq_f32_e32 v148, v148
	s_nop 0
	v_mul_f32_e32 v150, 0x45800000, v148
	v_cndmask_b32_e32 v149, v148, v150, vcc
	v_mul_f32_e32 v140, v149, v140
	v_mul_f32_e32 v141, v149, v141
	v_mul_f32_e32 v142, v149, v142
	v_mul_f32_e32 v143, v149, v143
	v_mul_f32_e32 v144, v149, v144
	v_mul_f32_e32 v145, v149, v145
	v_mul_f32_e32 v146, v149, v146
	v_mul_f32_e32 v147, v149, v147
	v_cvt_pk_bf16_f32 v140, v140, v141
	v_cvt_pk_bf16_f32 v141, v142, v143
	v_cvt_pk_bf16_f32 v142, v144, v145
	v_cvt_pk_bf16_f32 v143, v146, v147
	global_store_dwordx4 v[156:157], v[140:143], off
	s_waitcnt vmcnt(10)
; __device__ __forceinline__ unsigned cvt_pk_bf16(float lo, float hi) { unsigned r; asm volatile("v_cvt_pk_bf16_f32 %0, %1, %2" : "=v"(r) : "v"(lo), "v"(hi)); return r; }
; __device__ __forceinline__ float bf_lo(unsigned w) { return __uint_as_float(w << 16); }
; __device__ __forceinline__ float bf_hi(unsigned w) { return __uint_as_float(w & 0xffff0000u); }
; __global__ void __launch_bounds__(512, 2) trunk_fwd(Args args) {
;     ...
;                 for (int rr = 0; rr < 16; ++rr) {
;                     const int r = r0 + rr;
;                     const u32x4 gb = gb_n, gu = gu_n; const f32x4 pv4 = pv_n;
;                     if (rr < 15) { gb_n = *(const u32x4*)(Z + (size_t)(r + 1) * INP + 768 + c0); gu_n = *(const u32x4*)(Z + (size_t)(r + 1) * INP + 1280 + c0);
;                                    pv_n = *(const f32x4*)(pl + (size_t)(r + 1) * PLE + lane * 4); }
;                     float cv[8], uu[8]; float ss = 0.f;
; #pragma unroll
;                     for (int i = 0; i < 4; ++i) {
;                         uu[2 * i] = bf_lo(gu[i]); uu[2 * i + 1] = bf_hi(gu[i]);
;                         cv[2 * i] = bf_lo(gb[i]) * (w0[2 * i] * uu[2 * i] + w1[2 * i] * u1[2 * i] + w2[2 * i] * u2[2 * i]);
;                         cv[2 * i + 1] = bf_hi(gb[i]) * (w0[2 * i + 1] * uu[2 * i + 1] + w1[2 * i + 1] * u1[2 * i + 1] + w2[2 * i + 1] * u2[2 * i + 1]);
;                     }
; #pragma unroll
;                     for (int i = 0; i < 8; ++i) { ss += cv[i] * cv[i]; u2[i] = u1[i]; u1[i] = uu[i]; }
;                     ss = wave_sum(ss);
;                     const float rc = rsqrtf(ss * (1.0f / 512.0f) + EPS);
;                     u32x4 oc;
; #pragma unroll
;                     for (int i = 0; i < 4; ++i) oc[i] = cvt_pk_bf16(cv[2 * i] * rc, cv[2 * i + 1] * rc);
;                     *(u32x4*)(MIX + (size_t)r * 1024 + 512 + c0) = oc;
	v_lshlrev_b32_e32 v204, 16, v22
	v_and_b32_e32 v205, 0xffff0000, v22
	v_lshlrev_b32_e32 v206, 16, v23
	v_and_b32_e32 v207, 0xffff0000, v23
	v_lshlrev_b32_e32 v208, 16, v24
	v_and_b32_e32 v209, 0xffff0000, v24
	v_lshlrev_b32_e32 v210, 16, v25
	v_and_b32_e32 v211, 0xffff0000, v25
	v_mul_f32_e32 v140, v164, v204
	v_mul_f32_e32 v141, v165, v205
	v_mul_f32_e32 v142, v166, v206
	v_mul_f32_e32 v143, v167, v207
	v_mul_f32_e32 v144, v168, v208
	v_mul_f32_e32 v145, v169, v209
	v_mul_f32_e32 v146, v170, v210
	v_mul_f32_e32 v147, v171, v211
	v_fmac_f32_e32 v140, v172, v196
	v_fmac_f32_e32 v141, v173, v197
	v_fmac_f32_e32 v142, v174, v198
	v_fmac_f32_e32 v143, v175, v199
	v_fmac_f32_e32 v144, v176, v200
	v_fmac_f32_e32 v145, v177, v201
	v_fmac_f32_e32 v146, v178, v202
	v_fmac_f32_e32 v147, v179, v203
	v_fmac_f32_e32 v140, v180, v188
	v_fmac_f32_e32 v141, v181, v189
	v_fmac_f32_e32 v142, v182, v190
	v_fmac_f32_e32 v143, v183, v191
	v_fmac_f32_e32 v144, v184, v192
	v_fmac_f32_e32 v145, v185, v193
	v_fmac_f32_e32 v146, v186, v194
	v_fmac_f32_e32 v147, v187, v195
	v_lshlrev_b32_e32 v150, 16, v6
	v_and_b32_e32 v151, 0xffff0000, v6
	v_mul_f32_e32 v140, v150, v140
	v_mul_f32_e32 v141, v151, v141
	v_lshlrev_b32_e32 v150, 16, v7
	v_and_b32_e32 v151, 0xffff0000, v7
	v_mul_f32_e32 v142, v150, v142
	v_mul_f32_e32 v143, v151, v143
	v_lshlrev_b32_e32 v150, 16, v8
	v_and_b32_e32 v151, 0xffff0000, v8
	v_mul_f32_e32 v144, v150, v144
	v_mul_f32_e32 v145, v151, v145
	v_lshlrev_b32_e32 v150, 16, v9
	v_and_b32_e32 v151, 0xffff0000, v9
	v_mul_f32_e32 v146, v150, v146
	v_mul_f32_e32 v147, v151, v147
	v_mul_f32_e32 v148, v140, v140
	v_fmac_f32_e32 v148, v141, v141
	v_fmac_f32_e32 v148, v142, v142
	v_fmac_f32_e32 v148, v143, v143
	v_fmac_f32_e32 v148, v144, v144
	v_fmac_f32_e32 v148, v145, v145
	v_fmac_f32_e32 v148, v146, v146
	v_fmac_f32_e32 v148, v147, v147
	v_mad_i64_i32 v[152:153], vcc, s41, v221, v[58:59]
	s_add_u32 s41, s41, 1
	global_load_dwordx4 v[6:9], v[152:153], off offset:1536 nt
	global_load_dwordx4 v[22:25], v[152:153], off offset:2560 nt
	s_nop 1
	v_add_f32_dpp v148, v148, v148 quad_perm:[1,0,3,2] row_mask:0xf bank_mask:0xf
	s_nop 1
	v_add_f32_dpp v148, v148, v148 quad_perm:[2,3,0,1] row_mask:0xf bank_mask:0xf
	s_nop 1
	v_add_f32_dpp v148, v148, v148 row_half_mirror row_mask:0xf bank_mask:0xf
	s_nop 1
	v_add_f32_dpp v148, v148, v148 row_mirror row_mask:0xf bank_mask:0xf
	s_nop 1
	v_add_f32_dpp v148, v148, v148 row_bcast:15 row_mask:0xa bank_mask:0xf
	s_nop 1
	v_add_f32_dpp v148, v148, v148 row_bcast:31 row_mask:0xc bank_mask:0xf
	s_nop 0
	v_readlane_b32 s0, v148, 63
	s_nop 1
	v_mov_b32_e32 v148, s0
	v_fmamk_f32 v148, v148, 0x3b000000, v162
	v_mul_f32_e32 v150, 0x4b800000, v148
	v_cmp_gt_f32_e32 vcc, s31, v148
	s_nop 1
	v_cndmask_b32_e32 v148, v148, v150, vcc
	v_rsq_f32_e32 v148, v148
	s_nop 0
	v_mul_f32_e32 v150, 0x45800000, v148
	v_cndmask_b32_e32 v149, v148, v150, vcc
	v_mul_f32_e32 v140, v149, v140
	v_mul_f32_e32 v141, v149, v141
	v_mul_f32_e32 v142, v149, v142
	v_mul_f32_e32 v143, v149, v143
	v_mul_f32_e32 v144, v149, v144
	v_mul_f32_e32 v145, v149, v145
	v_mul_f32_e32 v146, v149, v146
	v_mul_f32_e32 v147, v149, v147
	v_cvt_pk_bf16_f32 v140, v140, v141
	v_cvt_pk_bf16_f32 v141, v142, v143
	v_cvt_pk_bf16_f32 v142, v144, v145
	v_cvt_pk_bf16_f32 v143, v146, v147
	global_store_dwordx4 v[156:157], v[140:143], off offset:2048
	v_lshl_add_u64 v[156:157], v[156:157], 0, s[20:21]
	s_waitcnt vmcnt(10)
	v_lshlrev_b32_e32 v188, 16, v26
	v_and_b32_e32 v189, 0xffff0000, v26
	v_lshlrev_b32_e32 v190, 16, v27
	v_and_b32_e32 v191, 0xffff0000, v27
	v_lshlrev_b32_e32 v192, 16, v28
	v_and_b32_e32 v193, 0xffff0000, v28
	v_lshlrev_b32_e32 v194, 16, v29
	v_and_b32_e32 v195, 0xffff0000, v29
	v_mul_f32_e32 v140, v164, v188
	v_mul_f32_e32 v141, v165, v189
	v_mul_f32_e32 v142, v166, v190
	v_mul_f32_e32 v143, v167, v191
	v_mul_f32_e32 v144, v168, v192
	v_mul_f32_e32 v145, v169, v193
	v_mul_f32_e32 v146, v170, v194
	v_mul_f32_e32 v147, v171, v195
	v_fmac_f32_e32 v140, v172, v204
	v_fmac_f32_e32 v141, v173, v205
	v_fmac_f32_e32 v142, v174, v206
	v_fmac_f32_e32 v143, v175, v207
	v_fmac_f32_e32 v144, v176, v208
	v_fmac_f32_e32 v145, v177, v209
	v_fmac_f32_e32 v146, v178, v210
	v_fmac_f32_e32 v147, v179, v211
	v_fmac_f32_e32 v140, v180, v196
	v_fmac_f32_e32 v141, v181, v197
	v_fmac_f32_e32 v142, v182, v198
	v_fmac_f32_e32 v143, v183, v199
	v_fmac_f32_e32 v144, v184, v200
	v_fmac_f32_e32 v145, v185, v201
	v_fmac_f32_e32 v146, v186, v202
	v_fmac_f32_e32 v147, v187, v203
	v_lshlrev_b32_e32 v150, 16, v10
	v_and_b32_e32 v151, 0xffff0000, v10
	v_mul_f32_e32 v140, v150, v140
	v_mul_f32_e32 v141, v151, v141
	v_lshlrev_b32_e32 v150, 16, v11
	v_and_b32_e32 v151, 0xffff0000, v11
	v_mul_f32_e32 v142, v150, v142
	v_mul_f32_e32 v143, v151, v143
	v_lshlrev_b32_e32 v150, 16, v12
	v_and_b32_e32 v151, 0xffff0000, v12
	v_mul_f32_e32 v144, v150, v144
	v_mul_f32_e32 v145, v151, v145
	v_lshlrev_b32_e32 v150, 16, v13
	v_and_b32_e32 v151, 0xffff0000, v13
	v_mul_f32_e32 v146, v150, v146
	v_mul_f32_e32 v147, v151, v147
	v_mul_f32_e32 v148, v140, v140
	v_fmac_f32_e32 v148, v141, v141
	v_fmac_f32_e32 v148, v142, v142
	v_fmac_f32_e32 v148, v143, v143
	v_fmac_f32_e32 v148, v144, v144
	v_fmac_f32_e32 v148, v145, v145
	v_fmac_f32_e32 v148, v146, v146
	v_fmac_f32_e32 v148, v147, v147
	v_mad_i64_i32 v[152:153], vcc, s41, v221, v[58:59]
	s_add_u32 s41, s41, 1
	global_load_dwordx4 v[10:13], v[152:153], off offset:1536 nt
	global_load_dwordx4 v[26:29], v[152:153], off offset:2560 nt
	s_nop 1
	v_add_f32_dpp v148, v148, v148 quad_perm:[1,0,3,2] row_mask:0xf bank_mask:0xf
	s_nop 1
	v_add_f32_dpp v148, v148, v148 quad_perm:[2,3,0,1] row_mask:0xf bank_mask:0xf
	s_nop 1
	v_add_f32_dpp v148, v148, v148 row_half_mirror row_mask:0xf bank_mask:0xf
	s_nop 1
	v_add_f32_dpp v148, v148, v148 row_mirror row_mask:0xf bank_mask:0xf
	s_nop 1
	v_add_f32_dpp v148, v148, v148 row_bcast:15 row_mask:0xa bank_mask:0xf
	s_nop 1
	v_add_f32_dpp v148, v148, v148 row_bcast:31 row_mask:0xc bank_mask:0xf
	s_nop 0
	v_readlane_b32 s0, v148, 63
	s_nop 1
	v_mov_b32_e32 v148, s0
	v_fmamk_f32 v148, v148, 0x3b000000, v162
	v_mul_f32_e32 v150, 0x4b800000, v148
	v_cmp_gt_f32_e32 vcc, s31, v148
	s_nop 1
	v_cndmask_b32_e32 v148, v148, v150, vcc
	v_rsq_f32_e32 v148, v148
	s_nop 0
	v_mul_f32_e32 v150, 0x45800000, v148
	v_cndmask_b32_e32 v149, v148, v150, vcc
	v_mul_f32_e32 v140, v149, v140
	v_mul_f32_e32 v141, v149, v141
	v_mul_f32_e32 v142, v149, v142
	v_mul_f32_e32 v143, v149, v143
	v_mul_f32_e32 v144, v149, v144
	v_mul_f32_e32 v145, v149, v145
	v_mul_f32_e32 v146, v149, v146
	v_mul_f32_e32 v147, v149, v147
	v_cvt_pk_bf16_f32 v140, v140, v141
	v_cvt_pk_bf16_f32 v141, v142, v143
	v_cvt_pk_bf16_f32 v142, v144, v145
	v_cvt_pk_bf16_f32 v143, v146, v147
	global_store_dwordx4 v[156:157], v[140:143], off
	s_waitcnt vmcnt(10)
; __device__ __forceinline__ unsigned cvt_pk_bf16(float lo, float hi) { unsigned r; asm volatile("v_cvt_pk_bf16_f32 %0, %1, %2" : "=v"(r) : "v"(lo), "v"(hi)); return r; }
; __device__ __forceinline__ float bf_lo(unsigned w) { return __uint_as_float(w << 16); }
; __device__ __forceinline__ float bf_hi(unsigned w) { return __uint_as_float(w & 0xffff0000u); }
; __global__ void __launch_bounds__(512, 2) trunk_fwd(Args args) {
;     ...
;                 for (int rr = 0; rr < 16; ++rr) {
;                     const int r = r0 + rr;
;                     const u32x4 gb = gb_n, gu = gu_n; const f32x4 pv4 = pv_n;
;                     if (rr < 15) { gb_n = *(const u32x4*)(Z + (size_t)(r + 1) * INP + 768 + c0); gu_n = *(const u32x4*)(Z + (size_t)(r + 1) * INP + 1280 + c0);
;                                    pv_n = *(const f32x4*)(pl + (size_t)(r + 1) * PLE + lane * 4); }
;                     float cv[8], uu[8]; float ss = 0.f;
; #pragma unroll
;                     for (int i = 0; i < 4; ++i) {
;                         uu[2 * i] = bf_lo(gu[i]); uu[2 * i + 1] = bf_hi(gu[i]);
;                         cv[2 * i] = bf_lo(gb[i]) * (w0[2 * i] * uu[2 * i] + w1[2 * i] * u1[2 * i] + w2[2 * i] * u2[2 * i]);
;                         cv[2 * i + 1] = bf_hi(gb[i]) * (w0[2 * i + 1] * uu[2 * i + 1] + w1[2 * i + 1] * u1[2 * i + 1] + w2[2 * i + 1] * u2[2 * i + 1]);
;                     }
; #pragma unroll
;                     for (int i = 0; i < 8; ++i) { ss += cv[i] * cv[i]; u2[i] = u1[i]; u1[i] = uu[i]; }
;                     ss = wave_sum(ss);
;                     const float rc = rsqrtf(ss * (1.0f / 512.0f) + EPS);
;                     u32x4 oc;
; #pragma unroll
;                     for (int i = 0; i < 4; ++i) oc[i] = cvt_pk_bf16(cv[2 * i] * rc, cv[2 * i + 1] * rc);
;                     *(u32x4*)(MIX + (size_t)r * 1024 + 512 + c0) = oc;
	v_lshlrev_b32_e32 v196, 16, v30
	v_and_b32_e32 v197, 0xffff0000, v30
	v_lshlrev_b32_e32 v198, 16, v31
	v_and_b32_e32 v199, 0xffff0000, v31
	v_lshlrev_b32_e32 v200, 16, v32
	v_and_b32_e32 v201, 0xffff0000, v32
	v_lshlrev_b32_e32 v202, 16, v33
	v_and_b32_e32 v203, 0xffff0000, v33
	v_mul_f32_e32 v140, v164, v196
	v_mul_f32_e32 v141, v165, v197
	v_mul_f32_e32 v142, v166, v198
	v_mul_f32_e32 v143, v167, v199
	v_mul_f32_e32 v144, v168, v200
	v_mul_f32_e32 v145, v169, v201
	v_mul_f32_e32 v146, v170, v202
	v_mul_f32_e32 v147, v171, v203
	v_fmac_f32_e32 v140, v172, v188
	v_fmac_f32_e32 v141, v173, v189
	v_fmac_f32_e32 v142, v174, v190
	v_fmac_f32_e32 v143, v175, v191
	v_fmac_f32_e32 v144, v176, v192
	v_fmac_f32_e32 v145, v177, v193
	v_fmac_f32_e32 v146, v178, v194
	v_fmac_f32_e32 v147, v179, v195
	v_fmac_f32_e32 v140, v180, v204
	v_fmac_f32_e32 v141, v181, v205
	v_fmac_f32_e32 v142, v182, v206
	v_fmac_f32_e32 v143, v183, v207
	v_fmac_f32_e32 v144, v184, v208
	v_fmac_f32_e32 v145, v185, v209
	v_fmac_f32_e32 v146, v186, v210
	v_fmac_f32_e32 v147, v187, v211
	v_lshlrev_b32_e32 v150, 16, v14
	v_and_b32_e32 v151, 0xffff0000, v14
	v_mul_f32_e32 v140, v150, v140
	v_mul_f32_e32 v141, v151, v141
	v_lshlrev_b32_e32 v150, 16, v15
	v_and_b32_e32 v151, 0xffff0000, v15
	v_mul_f32_e32 v142, v150, v142
	v_mul_f32_e32 v143, v151, v143
	v_lshlrev_b32_e32 v150, 16, v16
	v_and_b32_e32 v151, 0xffff0000, v16
	v_mul_f32_e32 v144, v150, v144
	v_mul_f32_e32 v145, v151, v145
	v_lshlrev_b32_e32 v150, 16, v17
	v_and_b32_e32 v151, 0xffff0000, v17
	v_mul_f32_e32 v146, v150, v146
	v_mul_f32_e32 v147, v151, v147
	v_mul_f32_e32 v148, v140, v140
	v_fmac_f32_e32 v148, v141, v141
	v_fmac_f32_e32 v148, v142, v142
	v_fmac_f32_e32 v148, v143, v143
	v_fmac_f32_e32 v148, v144, v144
	v_fmac_f32_e32 v148, v145, v145
	v_fmac_f32_e32 v148, v146, v146
	v_fmac_f32_e32 v148, v147, v147
	v_mad_i64_i32 v[152:153], vcc, s41, v221, v[58:59]
	s_add_u32 s41, s41, 1
	global_load_dwordx4 v[14:17], v[152:153], off offset:1536 nt
	global_load_dwordx4 v[30:33], v[152:153], off offset:2560 nt
	s_nop 1
	v_add_f32_dpp v148, v148, v148 quad_perm:[1,0,3,2] row_mask:0xf bank_mask:0xf
	s_nop 1
	v_add_f32_dpp v148, v148, v148 quad_perm:[2,3,0,1] row_mask:0xf bank_mask:0xf
	s_nop 1
	v_add_f32_dpp v148, v148, v148 row_half_mirror row_mask:0xf bank_mask:0xf
	s_nop 1
	v_add_f32_dpp v148, v148, v148 row_mirror row_mask:0xf bank_mask:0xf
	s_nop 1
	v_add_f32_dpp v148, v148, v148 row_bcast:15 row_mask:0xa bank_mask:0xf
	s_nop 1
	v_add_f32_dpp v148, v148, v148 row_bcast:31 row_mask:0xc bank_mask:0xf
	s_nop 0
	v_readlane_b32 s0, v148, 63
	s_nop 1
	v_mov_b32_e32 v148, s0
	v_fmamk_f32 v148, v148, 0x3b000000, v162
	v_mul_f32_e32 v150, 0x4b800000, v148
	v_cmp_gt_f32_e32 vcc, s31, v148
	s_nop 1
	v_cndmask_b32_e32 v148, v148, v150, vcc
	v_rsq_f32_e32 v148, v148
	s_nop 0
	v_mul_f32_e32 v150, 0x45800000, v148
	v_cndmask_b32_e32 v149, v148, v150, vcc
	v_mul_f32_e32 v140, v149, v140
	v_mul_f32_e32 v141, v149, v141
	v_mul_f32_e32 v142, v149, v142
	v_mul_f32_e32 v143, v149, v143
	v_mul_f32_e32 v144, v149, v144
	v_mul_f32_e32 v145, v149, v145
	v_mul_f32_e32 v146, v149, v146
	v_mul_f32_e32 v147, v149, v147
	v_cvt_pk_bf16_f32 v140, v140, v141
	v_cvt_pk_bf16_f32 v141, v142, v143
	v_cvt_pk_bf16_f32 v142, v144, v145
	v_cvt_pk_bf16_f32 v143, v146, v147
	global_store_dwordx4 v[156:157], v[140:143], off offset:2048
	v_lshl_add_u64 v[156:157], v[156:157], 0, s[20:21]
	s_waitcnt vmcnt(10)
	v_lshlrev_b32_e32 v204, 16, v18
	v_and_b32_e32 v205, 0xffff0000, v18
	v_lshlrev_b32_e32 v206, 16, v19
	v_and_b32_e32 v207, 0xffff0000, v19
	v_lshlrev_b32_e32 v208, 16, v20
	v_and_b32_e32 v209, 0xffff0000, v20
	v_lshlrev_b32_e32 v210, 16, v21
	v_and_b32_e32 v211, 0xffff0000, v21
	v_mul_f32_e32 v140, v164, v204
	v_mul_f32_e32 v141, v165, v205
	v_mul_f32_e32 v142, v166, v206
	v_mul_f32_e32 v143, v167, v207
	v_mul_f32_e32 v144, v168, v208
	v_mul_f32_e32 v145, v169, v209
	v_mul_f32_e32 v146, v170, v210
	v_mul_f32_e32 v147, v171, v211
	v_fmac_f32_e32 v140, v172, v196
	v_fmac_f32_e32 v141, v173, v197
	v_fmac_f32_e32 v142, v174, v198
	v_fmac_f32_e32 v143, v175, v199
	v_fmac_f32_e32 v144, v176, v200
	v_fmac_f32_e32 v145, v177, v201
	v_fmac_f32_e32 v146, v178, v202
	v_fmac_f32_e32 v147, v179, v203
	v_fmac_f32_e32 v140, v180, v188
	v_fmac_f32_e32 v141, v181, v189
	v_fmac_f32_e32 v142, v182, v190
	v_fmac_f32_e32 v143, v183, v191
	v_fmac_f32_e32 v144, v184, v192
	v_fmac_f32_e32 v145, v185, v193
	v_fmac_f32_e32 v146, v186, v194
	v_fmac_f32_e32 v147, v187, v195
	v_lshlrev_b32_e32 v150, 16, v2
	v_and_b32_e32 v151, 0xffff0000, v2
	v_mul_f32_e32 v140, v150, v140
	v_mul_f32_e32 v141, v151, v141
	v_lshlrev_b32_e32 v150, 16, v3
	v_and_b32_e32 v151, 0xffff0000, v3
	v_mul_f32_e32 v142, v150, v142
	v_mul_f32_e32 v143, v151, v143
	v_lshlrev_b32_e32 v150, 16, v4
	v_and_b32_e32 v151, 0xffff0000, v4
	v_mul_f32_e32 v144, v150, v144
	v_mul_f32_e32 v145, v151, v145
	v_lshlrev_b32_e32 v150, 16, v5
	v_and_b32_e32 v151, 0xffff0000, v5
	v_mul_f32_e32 v146, v150, v146
	v_mul_f32_e32 v147, v151, v147
	v_mul_f32_e32 v148, v140, v140
	v_fmac_f32_e32 v148, v141, v141
	v_fmac_f32_e32 v148, v142, v142
	v_fmac_f32_e32 v148, v143, v143
	v_fmac_f32_e32 v148, v144, v144
	v_fmac_f32_e32 v148, v145, v145
	v_fmac_f32_e32 v148, v146, v146
	v_fmac_f32_e32 v148, v147, v147
	v_mad_i64_i32 v[152:153], vcc, s41, v221, v[58:59]
	s_add_u32 s41, s41, 1
	global_load_dwordx4 v[2:5], v[152:153], off offset:1536 nt
	global_load_dwordx4 v[18:21], v[152:153], off offset:2560 nt
	s_nop 1
	v_add_f32_dpp v148, v148, v148 quad_perm:[1,0,3,2] row_mask:0xf bank_mask:0xf
	s_nop 1
	v_add_f32_dpp v148, v148, v148 quad_perm:[2,3,0,1] row_mask:0xf bank_mask:0xf
	s_nop 1
	v_add_f32_dpp v148, v148, v148 row_half_mirror row_mask:0xf bank_mask:0xf
	s_nop 1
	v_add_f32_dpp v148, v148, v148 row_mirror row_mask:0xf bank_mask:0xf
	s_nop 1
	v_add_f32_dpp v148, v148, v148 row_bcast:15 row_mask:0xa bank_mask:0xf
	s_nop 1
	v_add_f32_dpp v148, v148, v148 row_bcast:31 row_mask:0xc bank_mask:0xf
	s_nop 0
	v_readlane_b32 s0, v148, 63
	s_nop 1
	v_mov_b32_e32 v148, s0
	v_fmamk_f32 v148, v148, 0x3b000000, v162
	v_mul_f32_e32 v150, 0x4b800000, v148
	v_cmp_gt_f32_e32 vcc, s31, v148
	s_nop 1
	v_cndmask_b32_e32 v148, v148, v150, vcc
	v_rsq_f32_e32 v148, v148
	s_nop 0
	v_mul_f32_e32 v150, 0x45800000, v148
	v_cndmask_b32_e32 v149, v148, v150, vcc
	v_mul_f32_e32 v140, v149, v140
	v_mul_f32_e32 v141, v149, v141
	v_mul_f32_e32 v142, v149, v142
	v_mul_f32_e32 v143, v149, v143
	v_mul_f32_e32 v144, v149, v144
	v_mul_f32_e32 v145, v149, v145
	v_mul_f32_e32 v146, v149, v146
	v_mul_f32_e32 v147, v149, v147
	v_cvt_pk_bf16_f32 v140, v140, v141
	v_cvt_pk_bf16_f32 v141, v142, v143
	v_cvt_pk_bf16_f32 v142, v144, v145
	v_cvt_pk_bf16_f32 v143, v146, v147
	global_store_dwordx4 v[156:157], v[140:143], off
	s_waitcnt vmcnt(10)
; __device__ __forceinline__ unsigned cvt_pk_bf16(float lo, float hi) { unsigned r; asm volatile("v_cvt_pk_bf16_f32 %0, %1, %2" : "=v"(r) : "v"(lo), "v"(hi)); return r; }
; __device__ __forceinline__ float bf_lo(unsigned w) { return __uint_as_float(w << 16); }
; __device__ __forceinline__ float bf_hi(unsigned w) { return __uint_as_float(w & 0xffff0000u); }
; __global__ void __launch_bounds__(512, 2) trunk_fwd(Args args) {
;     ...
;                 for (int rr = 0; rr < 16; ++rr) {
;                     const int r = r0 + rr;
;                     const u32x4 gb = gb_n, gu = gu_n; const f32x4 pv4 = pv_n;
;                     if (rr < 15) { gb_n = *(const u32x4*)(Z + (size_t)(r + 1) * INP + 768 + c0); gu_n = *(const u32x4*)(Z + (size_t)(r + 1) * INP + 1280 + c0);
;                                    pv_n = *(const f32x4*)(pl + (size_t)(r + 1) * PLE + lane * 4); }
;                     float cv[8], uu[8]; float ss = 0.f;
; #pragma unroll
;                     for (int i = 0; i < 4; ++i) {
;                         uu[2 * i] = bf_lo(gu[i]); uu[2 * i + 1] = bf_hi(gu[i]);
;                         cv[2 * i] = bf_lo(gb[i]) * (w0[2 * i] * uu[2 * i] + w1[2 * i] * u1[2 * i] + w2[2 * i] * u2[2 * i]);
;                         cv[2 * i + 1] = bf_hi(gb[i]) * (w0[2 * i + 1] * uu[2 * i + 1] + w1[2 * i + 1] * u1[2 * i + 1] + w2[2 * i + 1] * u2[2 * i + 1]);
;                     }
; #pragma unroll
;                     for (int i = 0; i < 8; ++i) { ss += cv[i] * cv[i]; u2[i] = u1[i]; u1[i] = uu[i]; }
;                     ss = wave_sum(ss);
;                     const float rc = rsqrtf(ss * (1.0f / 512.0f) + EPS);
;                     u32x4 oc;
; #pragma unroll
;                     for (int i = 0; i < 4; ++i) oc[i] = cvt_pk_bf16(cv[2 * i] * rc, cv[2 * i + 1] * rc);
;                     *(u32x4*)(MIX + (size_t)r * 1024 + 512 + c0) = oc;
	v_lshlrev_b32_e32 v188, 16, v22
	v_and_b32_e32 v189, 0xffff0000, v22
	v_lshlrev_b32_e32 v190, 16, v23
	v_and_b32_e32 v191, 0xffff0000, v23
	v_lshlrev_b32_e32 v192, 16, v24
	v_and_b32_e32 v193, 0xffff0000, v24
	v_lshlrev_b32_e32 v194, 16, v25
	v_and_b32_e32 v195, 0xffff0000, v25
	v_mul_f32_e32 v140, v164, v188
	v_mul_f32_e32 v141, v165, v189
	v_mul_f32_e32 v142, v166, v190
	v_mul_f32_e32 v143, v167, v191
	v_mul_f32_e32 v144, v168, v192
	v_mul_f32_e32 v145, v169, v193
	v_mul_f32_e32 v146, v170, v194
	v_mul_f32_e32 v147, v171, v195
	v_fmac_f32_e32 v140, v172, v204
	v_fmac_f32_e32 v141, v173, v205
	v_fmac_f32_e32 v142, v174, v206
	v_fmac_f32_e32 v143, v175, v207
	v_fmac_f32_e32 v144, v176, v208
	v_fmac_f32_e32 v145, v177, v209
	v_fmac_f32_e32 v146, v178, v210
	v_fmac_f32_e32 v147, v179, v211
	v_fmac_f32_e32 v140, v180, v196
	v_fmac_f32_e32 v141, v181, v197
	v_fmac_f32_e32 v142, v182, v198
	v_fmac_f32_e32 v143, v183, v199
	v_fmac_f32_e32 v144, v184, v200
	v_fmac_f32_e32 v145, v185, v201
	v_fmac_f32_e32 v146, v186, v202
	v_fmac_f32_e32 v147, v187, v203
	v_lshlrev_b32_e32 v150, 16, v6
	v_and_b32_e32 v151, 0xffff0000, v6
	v_mul_f32_e32 v140, v150, v140
	v_mul_f32_e32 v141, v151, v141
	v_lshlrev_b32_e32 v150, 16, v7
	v_and_b32_e32 v151, 0xffff0000, v7
	v_mul_f32_e32 v142, v150, v142
	v_mul_f32_e32 v143, v151, v143
	v_lshlrev_b32_e32 v150, 16, v8
	v_and_b32_e32 v151, 0xffff0000, v8
	v_mul_f32_e32 v144, v150, v144
	v_mul_f32_e32 v145, v151, v145
	v_lshlrev_b32_e32 v150, 16, v9
	v_and_b32_e32 v151, 0xffff0000, v9
	v_mul_f32_e32 v146, v150, v146
	v_mul_f32_e32 v147, v151, v147
	v_mul_f32_e32 v148, v140, v140
	v_fmac_f32_e32 v148, v141, v141
	v_fmac_f32_e32 v148, v142, v142
	v_fmac_f32_e32 v148, v143, v143
	v_fmac_f32_e32 v148, v144, v144
	v_fmac_f32_e32 v148, v145, v145
	v_fmac_f32_e32 v148, v146, v146
	v_fmac_f32_e32 v148, v147, v147
	v_mad_i64_i32 v[152:153], vcc, s41, v221, v[58:59]
	s_add_u32 s41, s41, 1
	global_load_dwordx4 v[6:9], v[152:153], off offset:1536 nt
	global_load_dwordx4 v[22:25], v[152:153], off offset:2560 nt
	s_nop 1
	v_add_f32_dpp v148, v148, v148 quad_perm:[1,0,3,2] row_mask:0xf bank_mask:0xf
	s_nop 1
	v_add_f32_dpp v148, v148, v148 quad_perm:[2,3,0,1] row_mask:0xf bank_mask:0xf
	s_nop 1
	v_add_f32_dpp v148, v148, v148 row_half_mirror row_mask:0xf bank_mask:0xf
	s_nop 1
	v_add_f32_dpp v148, v148, v148 row_mirror row_mask:0xf bank_mask:0xf
	s_nop 1
	v_add_f32_dpp v148, v148, v148 row_bcast:15 row_mask:0xa bank_mask:0xf
	s_nop 1
	v_add_f32_dpp v148, v148, v148 row_bcast:31 row_mask:0xc bank_mask:0xf
	s_nop 0
	v_readlane_b32 s0, v148, 63
	s_nop 1
	v_mov_b32_e32 v148, s0
	v_fmamk_f32 v148, v148, 0x3b000000, v162
	v_mul_f32_e32 v150, 0x4b800000, v148
	v_cmp_gt_f32_e32 vcc, s31, v148
	s_nop 1
	v_cndmask_b32_e32 v148, v148, v150, vcc
	v_rsq_f32_e32 v148, v148
	s_nop 0
	v_mul_f32_e32 v150, 0x45800000, v148
	v_cndmask_b32_e32 v149, v148, v150, vcc
	v_mul_f32_e32 v140, v149, v140
	v_mul_f32_e32 v141, v149, v141
	v_mul_f32_e32 v142, v149, v142
	v_mul_f32_e32 v143, v149, v143
	v_mul_f32_e32 v144, v149, v144
	v_mul_f32_e32 v145, v149, v145
	v_mul_f32_e32 v146, v149, v146
	v_mul_f32_e32 v147, v149, v147
	v_cvt_pk_bf16_f32 v140, v140, v141
	v_cvt_pk_bf16_f32 v141, v142, v143
	v_cvt_pk_bf16_f32 v142, v144, v145
	v_cvt_pk_bf16_f32 v143, v146, v147
	global_store_dwordx4 v[156:157], v[140:143], off offset:2048
	v_lshl_add_u64 v[156:157], v[156:157], 0, s[20:21]
	s_waitcnt vmcnt(10)
	v_lshlrev_b32_e32 v196, 16, v26
	v_and_b32_e32 v197, 0xffff0000, v26
	v_lshlrev_b32_e32 v198, 16, v27
	v_and_b32_e32 v199, 0xffff0000, v27
	v_lshlrev_b32_e32 v200, 16, v28
	v_and_b32_e32 v201, 0xffff0000, v28
	v_lshlrev_b32_e32 v202, 16, v29
	v_and_b32_e32 v203, 0xffff0000, v29
	v_mul_f32_e32 v140, v164, v196
	v_mul_f32_e32 v141, v165, v197
	v_mul_f32_e32 v142, v166, v198
	v_mul_f32_e32 v143, v167, v199
	v_mul_f32_e32 v144, v168, v200
	v_mul_f32_e32 v145, v169, v201
	v_mul_f32_e32 v146, v170, v202
	v_mul_f32_e32 v147, v171, v203
	v_fmac_f32_e32 v140, v172, v188
	v_fmac_f32_e32 v141, v173, v189
	v_fmac_f32_e32 v142, v174, v190
	v_fmac_f32_e32 v143, v175, v191
	v_fmac_f32_e32 v144, v176, v192
	v_fmac_f32_e32 v145, v177, v193
	v_fmac_f32_e32 v146, v178, v194
	v_fmac_f32_e32 v147, v179, v195
	v_fmac_f32_e32 v140, v180, v204
	v_fmac_f32_e32 v141, v181, v205
	v_fmac_f32_e32 v142, v182, v206
	v_fmac_f32_e32 v143, v183, v207
	v_fmac_f32_e32 v144, v184, v208
	v_fmac_f32_e32 v145, v185, v209
	v_fmac_f32_e32 v146, v186, v210
	v_fmac_f32_e32 v147, v187, v211
	v_lshlrev_b32_e32 v150, 16, v10
	v_and_b32_e32 v151, 0xffff0000, v10
	v_mul_f32_e32 v140, v150, v140
	v_mul_f32_e32 v141, v151, v141
	v_lshlrev_b32_e32 v150, 16, v11
	v_and_b32_e32 v151, 0xffff0000, v11
	v_mul_f32_e32 v142, v150, v142
	v_mul_f32_e32 v143, v151, v143
	v_lshlrev_b32_e32 v150, 16, v12
	v_and_b32_e32 v151, 0xffff0000, v12
	v_mul_f32_e32 v144, v150, v144
	v_mul_f32_e32 v145, v151, v145
	v_lshlrev_b32_e32 v150, 16, v13
	v_and_b32_e32 v151, 0xffff0000, v13
	v_mul_f32_e32 v146, v150, v146
	v_mul_f32_e32 v147, v151, v147
	v_mul_f32_e32 v148, v140, v140
	v_fmac_f32_e32 v148, v141, v141
	v_fmac_f32_e32 v148, v142, v142
	v_fmac_f32_e32 v148, v143, v143
	v_fmac_f32_e32 v148, v144, v144
	v_fmac_f32_e32 v148, v145, v145
	v_fmac_f32_e32 v148, v146, v146
	v_fmac_f32_e32 v148, v147, v147
	v_mad_i64_i32 v[152:153], vcc, s41, v221, v[58:59]
	s_add_u32 s41, s41, 1
	global_load_dwordx4 v[10:13], v[152:153], off offset:1536 nt
	global_load_dwordx4 v[26:29], v[152:153], off offset:2560 nt
	s_nop 1
	v_add_f32_dpp v148, v148, v148 quad_perm:[1,0,3,2] row_mask:0xf bank_mask:0xf
	s_nop 1
	v_add_f32_dpp v148, v148, v148 quad_perm:[2,3,0,1] row_mask:0xf bank_mask:0xf
	s_nop 1
	v_add_f32_dpp v148, v148, v148 row_half_mirror row_mask:0xf bank_mask:0xf
	s_nop 1
	v_add_f32_dpp v148, v148, v148 row_mirror row_mask:0xf bank_mask:0xf
	s_nop 1
	v_add_f32_dpp v148, v148, v148 row_bcast:15 row_mask:0xa bank_mask:0xf
	s_nop 1
	v_add_f32_dpp v148, v148, v148 row_bcast:31 row_mask:0xc bank_mask:0xf
	s_nop 0
	v_readlane_b32 s0, v148, 63
	s_nop 1
	v_mov_b32_e32 v148, s0
	v_fmamk_f32 v148, v148, 0x3b000000, v162
	v_mul_f32_e32 v150, 0x4b800000, v148
	v_cmp_gt_f32_e32 vcc, s31, v148
	s_nop 1
	v_cndmask_b32_e32 v148, v148, v150, vcc
	v_rsq_f32_e32 v148, v148
	s_nop 0
	v_mul_f32_e32 v150, 0x45800000, v148
	v_cndmask_b32_e32 v149, v148, v150, vcc
	v_mul_f32_e32 v140, v149, v140
	v_mul_f32_e32 v141, v149, v141
	v_mul_f32_e32 v142, v149, v142
	v_mul_f32_e32 v143, v149, v143
	v_mul_f32_e32 v144, v149, v144
	v_mul_f32_e32 v145, v149, v145
	v_mul_f32_e32 v146, v149, v146
	v_mul_f32_e32 v147, v149, v147
	v_cvt_pk_bf16_f32 v140, v140, v141
	v_cvt_pk_bf16_f32 v141, v142, v143
	v_cvt_pk_bf16_f32 v142, v144, v145
	v_cvt_pk_bf16_f32 v143, v146, v147
	global_store_dwordx4 v[156:157], v[140:143], off
	s_waitcnt vmcnt(10)
; __device__ __forceinline__ unsigned cvt_pk_bf16(float lo, float hi) { unsigned r; asm volatile("v_cvt_pk_bf16_f32 %0, %1, %2" : "=v"(r) : "v"(lo), "v"(hi)); return r; }
; __device__ __forceinline__ float bf_lo(unsigned w) { return __uint_as_float(w << 16); }
; __device__ __forceinline__ float bf_hi(unsigned w) { return __uint_as_float(w & 0xffff0000u); }
; __global__ void __launch_bounds__(512, 2) trunk_fwd(Args args) {
;     ...
;                 for (int rr = 0; rr < 16; ++rr) {
;                     const int r = r0 + rr;
;                     const u32x4 gb = gb_n, gu = gu_n; const f32x4 pv4 = pv_n;
;                     if (rr < 15) { gb_n = *(const u32x4*)(Z + (size_t)(r + 1) * INP + 768 + c0); gu_n = *(const u32x4*)(Z + (size_t)(r + 1) * INP + 1280 + c0);
;                                    pv_n = *(const f32x4*)(pl + (size_t)(r + 1) * PLE + lane * 4); }
;                     float cv[8], uu[8]; float ss = 0.f;
; #pragma unroll
;                     for (int i = 0; i < 4; ++i) {
;                         uu[2 * i] = bf_lo(gu[i]); uu[2 * i + 1] = bf_hi(gu[i]);
;                         cv[2 * i] = bf_lo(gb[i]) * (w0[2 * i] * uu[2 * i] + w1[2 * i] * u1[2 * i] + w2[2 * i] * u2[2 * i]);
;                         cv[2 * i + 1] = bf_hi(gb[i]) * (w0[2 * i + 1] * uu[2 * i + 1] + w1[2 * i + 1] * u1[2 * i + 1] + w2[2 * i + 1] * u2[2 * i + 1]);
;                     }
; #pragma unroll
;                     for (int i = 0; i < 8; ++i) { ss += cv[i] * cv[i]; u2[i] = u1[i]; u1[i] = uu[i]; }
;                     ss = wave_sum(ss);
;                     const float rc = rsqrtf(ss * (1.0f / 512.0f) + EPS);
;                     u32x4 oc;
; #pragma unroll
;                     for (int i = 0; i < 4; ++i) oc[i] = cvt_pk_bf16(cv[2 * i] * rc, cv[2 * i + 1] * rc);
;                     *(u32x4*)(MIX + (size_t)r * 1024 + 512 + c0) = oc;
	v_lshlrev_b32_e32 v204, 16, v30
	v_and_b32_e32 v205, 0xffff0000, v30
	v_lshlrev_b32_e32 v206, 16, v31
	v_and_b32_e32 v207, 0xffff0000, v31
	v_lshlrev_b32_e32 v208, 16, v32
	v_and_b32_e32 v209, 0xffff0000, v32
	v_lshlrev_b32_e32 v210, 16, v33
	v_and_b32_e32 v211, 0xffff0000, v33
	v_mul_f32_e32 v140, v164, v204
	v_mul_f32_e32 v141, v165, v205
	v_mul_f32_e32 v142, v166, v206
	v_mul_f32_e32 v143, v167, v207
	v_mul_f32_e32 v144, v168, v208
	v_mul_f32_e32 v145, v169, v209
	v_mul_f32_e32 v146, v170, v210
	v_mul_f32_e32 v147, v171, v211
	v_fmac_f32_e32 v140, v172, v196
	v_fmac_f32_e32 v141, v173, v197
	v_fmac_f32_e32 v142, v174, v198
	v_fmac_f32_e32 v143, v175, v199
	v_fmac_f32_e32 v144, v176, v200
	v_fmac_f32_e32 v145, v177, v201
	v_fmac_f32_e32 v146, v178, v202
	v_fmac_f32_e32 v147, v179, v203
	v_fmac_f32_e32 v140, v180, v188
	v_fmac_f32_e32 v141, v181, v189
	v_fmac_f32_e32 v142, v182, v190
	v_fmac_f32_e32 v143, v183, v191
	v_fmac_f32_e32 v144, v184, v192
	v_fmac_f32_e32 v145, v185, v193
	v_fmac_f32_e32 v146, v186, v194
	v_fmac_f32_e32 v147, v187, v195
	v_lshlrev_b32_e32 v150, 16, v14
	v_and_b32_e32 v151, 0xffff0000, v14
	v_mul_f32_e32 v140, v150, v140
	v_mul_f32_e32 v141, v151, v141
	v_lshlrev_b32_e32 v150, 16, v15
	v_and_b32_e32 v151, 0xffff0000, v15
	v_mul_f32_e32 v142, v150, v142
	v_mul_f32_e32 v143, v151, v143
	v_lshlrev_b32_e32 v150, 16, v16
	v_and_b32_e32 v151, 0xffff0000, v16
	v_mul_f32_e32 v144, v150, v144
	v_mul_f32_e32 v145, v151, v145
	v_lshlrev_b32_e32 v150, 16, v17
	v_and_b32_e32 v151, 0xffff0000, v17
	v_mul_f32_e32 v146, v150, v146
	v_mul_f32_e32 v147, v151, v147
	v_mul_f32_e32 v148, v140, v140
	v_fmac_f32_e32 v148, v141, v141
	v_fmac_f32_e32 v148, v142, v142
	v_fmac_f32_e32 v148, v143, v143
	v_fmac_f32_e32 v148, v144, v144
	v_fmac_f32_e32 v148, v145, v145
	v_fmac_f32_e32 v148, v146, v146
	v_fmac_f32_e32 v148, v147, v147
	v_mad_i64_i32 v[152:153], vcc, s41, v221, v[58:59]
	s_add_u32 s41, s41, 1
	global_load_dwordx4 v[14:17], v[152:153], off offset:1536 nt
	global_load_dwordx4 v[30:33], v[152:153], off offset:2560 nt
	s_nop 1
	v_add_f32_dpp v148, v148, v148 quad_perm:[1,0,3,2] row_mask:0xf bank_mask:0xf
	s_nop 1
	v_add_f32_dpp v148, v148, v148 quad_perm:[2,3,0,1] row_mask:0xf bank_mask:0xf
	s_nop 1
	v_add_f32_dpp v148, v148, v148 row_half_mirror row_mask:0xf bank_mask:0xf
	s_nop 1
	v_add_f32_dpp v148, v148, v148 row_mirror row_mask:0xf bank_mask:0xf
	s_nop 1
	v_add_f32_dpp v148, v148, v148 row_bcast:15 row_mask:0xa bank_mask:0xf
	s_nop 1
	v_add_f32_dpp v148, v148, v148 row_bcast:31 row_mask:0xc bank_mask:0xf
	s_nop 0
	v_readlane_b32 s0, v148, 63
	s_nop 1
	v_mov_b32_e32 v148, s0
	v_fmamk_f32 v148, v148, 0x3b000000, v162
	v_mul_f32_e32 v150, 0x4b800000, v148
	v_cmp_gt_f32_e32 vcc, s31, v148
	s_nop 1
	v_cndmask_b32_e32 v148, v148, v150, vcc
	v_rsq_f32_e32 v148, v148
	s_nop 0
	v_mul_f32_e32 v150, 0x45800000, v148
	v_cndmask_b32_e32 v149, v148, v150, vcc
	v_mul_f32_e32 v140, v149, v140
	v_mul_f32_e32 v141, v149, v141
	v_mul_f32_e32 v142, v149, v142
	v_mul_f32_e32 v143, v149, v143
	v_mul_f32_e32 v144, v149, v144
	v_mul_f32_e32 v145, v149, v145
	v_mul_f32_e32 v146, v149, v146
	v_mul_f32_e32 v147, v149, v147
	v_cvt_pk_bf16_f32 v140, v140, v141
	v_cvt_pk_bf16_f32 v141, v142, v143
	v_cvt_pk_bf16_f32 v142, v144, v145
	v_cvt_pk_bf16_f32 v143, v146, v147
	global_store_dwordx4 v[156:157], v[140:143], off offset:2048
	v_lshl_add_u64 v[156:157], v[156:157], 0, s[20:21]
	s_waitcnt vmcnt(10)
	v_lshlrev_b32_e32 v188, 16, v18
	v_and_b32_e32 v189, 0xffff0000, v18
	v_lshlrev_b32_e32 v190, 16, v19
	v_and_b32_e32 v191, 0xffff0000, v19
	v_lshlrev_b32_e32 v192, 16, v20
	v_and_b32_e32 v193, 0xffff0000, v20
	v_lshlrev_b32_e32 v194, 16, v21
	v_and_b32_e32 v195, 0xffff0000, v21
	v_mul_f32_e32 v140, v164, v188
	v_mul_f32_e32 v141, v165, v189
	v_mul_f32_e32 v142, v166, v190
	v_mul_f32_e32 v143, v167, v191
	v_mul_f32_e32 v144, v168, v192
	v_mul_f32_e32 v145, v169, v193
	v_mul_f32_e32 v146, v170, v194
	v_mul_f32_e32 v147, v171, v195
	v_fmac_f32_e32 v140, v172, v204
	v_fmac_f32_e32 v141, v173, v205
	v_fmac_f32_e32 v142, v174, v206
	v_fmac_f32_e32 v143, v175, v207
	v_fmac_f32_e32 v144, v176, v208
	v_fmac_f32_e32 v145, v177, v209
	v_fmac_f32_e32 v146, v178, v210
	v_fmac_f32_e32 v147, v179, v211
	v_fmac_f32_e32 v140, v180, v196
	v_fmac_f32_e32 v141, v181, v197
	v_fmac_f32_e32 v142, v182, v198
	v_fmac_f32_e32 v143, v183, v199
	v_fmac_f32_e32 v144, v184, v200
	v_fmac_f32_e32 v145, v185, v201
	v_fmac_f32_e32 v146, v186, v202
	v_fmac_f32_e32 v147, v187, v203
	v_lshlrev_b32_e32 v150, 16, v2
	v_and_b32_e32 v151, 0xffff0000, v2
	v_mul_f32_e32 v140, v150, v140
	v_mul_f32_e32 v141, v151, v141
	v_lshlrev_b32_e32 v150, 16, v3
	v_and_b32_e32 v151, 0xffff0000, v3
	v_mul_f32_e32 v142, v150, v142
	v_mul_f32_e32 v143, v151, v143
	v_lshlrev_b32_e32 v150, 16, v4
	v_and_b32_e32 v151, 0xffff0000, v4
	v_mul_f32_e32 v144, v150, v144
	v_mul_f32_e32 v145, v151, v145
	v_lshlrev_b32_e32 v150, 16, v5
	v_and_b32_e32 v151, 0xffff0000, v5
	v_mul_f32_e32 v146, v150, v146
	v_mul_f32_e32 v147, v151, v147
	v_mul_f32_e32 v148, v140, v140
	v_fmac_f32_e32 v148, v141, v141
	v_fmac_f32_e32 v148, v142, v142
	v_fmac_f32_e32 v148, v143, v143
	v_fmac_f32_e32 v148, v144, v144
	v_fmac_f32_e32 v148, v145, v145
	v_fmac_f32_e32 v148, v146, v146
	v_fmac_f32_e32 v148, v147, v147
	s_nop 1
	v_add_f32_dpp v148, v148, v148 quad_perm:[1,0,3,2] row_mask:0xf bank_mask:0xf
	s_nop 1
	v_add_f32_dpp v148, v148, v148 quad_perm:[2,3,0,1] row_mask:0xf bank_mask:0xf
	s_nop 1
	v_add_f32_dpp v148, v148, v148 row_half_mirror row_mask:0xf bank_mask:0xf
	s_nop 1
	v_add_f32_dpp v148, v148, v148 row_mirror row_mask:0xf bank_mask:0xf
	s_nop 1
	v_add_f32_dpp v148, v148, v148 row_bcast:15 row_mask:0xa bank_mask:0xf
	s_nop 1
	v_add_f32_dpp v148, v148, v148 row_bcast:31 row_mask:0xc bank_mask:0xf
	s_nop 0
	v_readlane_b32 s0, v148, 63
	s_nop 1
	v_mov_b32_e32 v148, s0
	v_fmamk_f32 v148, v148, 0x3b000000, v162
	v_mul_f32_e32 v150, 0x4b800000, v148
	v_cmp_gt_f32_e32 vcc, s31, v148
	s_nop 1
	v_cndmask_b32_e32 v148, v148, v150, vcc
	v_rsq_f32_e32 v148, v148
	s_nop 0
	v_mul_f32_e32 v150, 0x45800000, v148
	v_cndmask_b32_e32 v149, v148, v150, vcc
	v_mul_f32_e32 v140, v149, v140
	v_mul_f32_e32 v141, v149, v141
	v_mul_f32_e32 v142, v149, v142
	v_mul_f32_e32 v143, v149, v143
	v_mul_f32_e32 v144, v149, v144
	v_mul_f32_e32 v145, v149, v145
	v_mul_f32_e32 v146, v149, v146
	v_mul_f32_e32 v147, v149, v147
	v_cvt_pk_bf16_f32 v140, v140, v141
	v_cvt_pk_bf16_f32 v141, v142, v143
	v_cvt_pk_bf16_f32 v142, v144, v145
	v_cvt_pk_bf16_f32 v143, v146, v147
	global_store_dwordx4 v[156:157], v[140:143], off
	s_waitcnt vmcnt(8)
; __device__ __forceinline__ unsigned cvt_pk_bf16(float lo, float hi) { unsigned r; asm volatile("v_cvt_pk_bf16_f32 %0, %1, %2" : "=v"(r) : "v"(lo), "v"(hi)); return r; }
; __device__ __forceinline__ float bf_lo(unsigned w) { return __uint_as_float(w << 16); }
; __device__ __forceinline__ float bf_hi(unsigned w) { return __uint_as_float(w & 0xffff0000u); }
; __global__ void __launch_bounds__(512, 2) trunk_fwd(Args args) {
;     ...
;                 for (int rr = 0; rr < 16; ++rr) {
;                     const int r = r0 + rr;
;                     const u32x4 gb = gb_n, gu = gu_n; const f32x4 pv4 = pv_n;
;                     if (rr < 15) { gb_n = *(const u32x4*)(Z + (size_t)(r + 1) * INP + 768 + c0); gu_n = *(const u32x4*)(Z + (size_t)(r + 1) * INP + 1280 + c0);
;                                    pv_n = *(const f32x4*)(pl + (size_t)(r + 1) * PLE + lane * 4); }
;                     float cv[8], uu[8]; float ss = 0.f;
; #pragma unroll
;                     for (int i = 0; i < 4; ++i) {
;                         uu[2 * i] = bf_lo(gu[i]); uu[2 * i + 1] = bf_hi(gu[i]);
;                         cv[2 * i] = bf_lo(gb[i]) * (w0[2 * i] * uu[2 * i] + w1[2 * i] * u1[2 * i] + w2[2 * i] * u2[2 * i]);
;                         cv[2 * i + 1] = bf_hi(gb[i]) * (w0[2 * i + 1] * uu[2 * i + 1] + w1[2 * i + 1] * u1[2 * i + 1] + w2[2 * i + 1] * u2[2 * i + 1]);
;                     }
; #pragma unroll
;                     for (int i = 0; i < 8; ++i) { ss += cv[i] * cv[i]; u2[i] = u1[i]; u1[i] = uu[i]; }
;                     ss = wave_sum(ss);
;                     const float rc = rsqrtf(ss * (1.0f / 512.0f) + EPS);
;                     u32x4 oc;
; #pragma unroll
;                     for (int i = 0; i < 4; ++i) oc[i] = cvt_pk_bf16(cv[2 * i] * rc, cv[2 * i + 1] * rc);
;                     *(u32x4*)(MIX + (size_t)r * 1024 + 512 + c0) = oc;
	v_lshlrev_b32_e32 v196, 16, v22
	v_and_b32_e32 v197, 0xffff0000, v22
	v_lshlrev_b32_e32 v198, 16, v23
	v_and_b32_e32 v199, 0xffff0000, v23
	v_lshlrev_b32_e32 v200, 16, v24
	v_and_b32_e32 v201, 0xffff0000, v24
	v_lshlrev_b32_e32 v202, 16, v25
	v_and_b32_e32 v203, 0xffff0000, v25
	v_mul_f32_e32 v140, v164, v196
	v_mul_f32_e32 v141, v165, v197
	v_mul_f32_e32 v142, v166, v198
	v_mul_f32_e32 v143, v167, v199
	v_mul_f32_e32 v144, v168, v200
	v_mul_f32_e32 v145, v169, v201
	v_mul_f32_e32 v146, v170, v202
	v_mul_f32_e32 v147, v171, v203
	v_fmac_f32_e32 v140, v172, v188
	v_fmac_f32_e32 v141, v173, v189
	v_fmac_f32_e32 v142, v174, v190
	v_fmac_f32_e32 v143, v175, v191
	v_fmac_f32_e32 v144, v176, v192
	v_fmac_f32_e32 v145, v177, v193
	v_fmac_f32_e32 v146, v178, v194
	v_fmac_f32_e32 v147, v179, v195
	v_fmac_f32_e32 v140, v180, v204
	v_fmac_f32_e32 v141, v181, v205
	v_fmac_f32_e32 v142, v182, v206
	v_fmac_f32_e32 v143, v183, v207
	v_fmac_f32_e32 v144, v184, v208
	v_fmac_f32_e32 v145, v185, v209
	v_fmac_f32_e32 v146, v186, v210
	v_fmac_f32_e32 v147, v187, v211
	v_lshlrev_b32_e32 v150, 16, v6
	v_and_b32_e32 v151, 0xffff0000, v6
	v_mul_f32_e32 v140, v150, v140
	v_mul_f32_e32 v141, v151, v141
	v_lshlrev_b32_e32 v150, 16, v7
	v_and_b32_e32 v151, 0xffff0000, v7
	v_mul_f32_e32 v142, v150, v142
	v_mul_f32_e32 v143, v151, v143
	v_lshlrev_b32_e32 v150, 16, v8
	v_and_b32_e32 v151, 0xffff0000, v8
	v_mul_f32_e32 v144, v150, v144
	v_mul_f32_e32 v145, v151, v145
	v_lshlrev_b32_e32 v150, 16, v9
	v_and_b32_e32 v151, 0xffff0000, v9
	v_mul_f32_e32 v146, v150, v146
	v_mul_f32_e32 v147, v151, v147
	v_mul_f32_e32 v148, v140, v140
	v_fmac_f32_e32 v148, v141, v141
	v_fmac_f32_e32 v148, v142, v142
	v_fmac_f32_e32 v148, v143, v143
	v_fmac_f32_e32 v148, v144, v144
	v_fmac_f32_e32 v148, v145, v145
	v_fmac_f32_e32 v148, v146, v146
	v_fmac_f32_e32 v148, v147, v147
	s_nop 1
	v_add_f32_dpp v148, v148, v148 quad_perm:[1,0,3,2] row_mask:0xf bank_mask:0xf
	s_nop 1
	v_add_f32_dpp v148, v148, v148 quad_perm:[2,3,0,1] row_mask:0xf bank_mask:0xf
	s_nop 1
	v_add_f32_dpp v148, v148, v148 row_half_mirror row_mask:0xf bank_mask:0xf
	s_nop 1
	v_add_f32_dpp v148, v148, v148 row_mirror row_mask:0xf bank_mask:0xf
	s_nop 1
	v_add_f32_dpp v148, v148, v148 row_bcast:15 row_mask:0xa bank_mask:0xf
	s_nop 1
	v_add_f32_dpp v148, v148, v148 row_bcast:31 row_mask:0xc bank_mask:0xf
	s_nop 0
	v_readlane_b32 s0, v148, 63
	s_nop 1
	v_mov_b32_e32 v148, s0
	v_fmamk_f32 v148, v148, 0x3b000000, v162
	v_mul_f32_e32 v150, 0x4b800000, v148
	v_cmp_gt_f32_e32 vcc, s31, v148
	s_nop 1
	v_cndmask_b32_e32 v148, v148, v150, vcc
	v_rsq_f32_e32 v148, v148
	s_nop 0
	v_mul_f32_e32 v150, 0x45800000, v148
	v_cndmask_b32_e32 v149, v148, v150, vcc
	v_mul_f32_e32 v140, v149, v140
	v_mul_f32_e32 v141, v149, v141
	v_mul_f32_e32 v142, v149, v142
	v_mul_f32_e32 v143, v149, v143
	v_mul_f32_e32 v144, v149, v144
	v_mul_f32_e32 v145, v149, v145
	v_mul_f32_e32 v146, v149, v146
	v_mul_f32_e32 v147, v149, v147
	v_cvt_pk_bf16_f32 v140, v140, v141
	v_cvt_pk_bf16_f32 v141, v142, v143
	v_cvt_pk_bf16_f32 v142, v144, v145
	v_cvt_pk_bf16_f32 v143, v146, v147
	global_store_dwordx4 v[156:157], v[140:143], off offset:2048
	v_lshl_add_u64 v[156:157], v[156:157], 0, s[20:21]
	s_waitcnt vmcnt(6)
	v_lshlrev_b32_e32 v204, 16, v26
	v_and_b32_e32 v205, 0xffff0000, v26
	v_lshlrev_b32_e32 v206, 16, v27
	v_and_b32_e32 v207, 0xffff0000, v27
	v_lshlrev_b32_e32 v208, 16, v28
	v_and_b32_e32 v209, 0xffff0000, v28
	v_lshlrev_b32_e32 v210, 16, v29
	v_and_b32_e32 v211, 0xffff0000, v29
	v_mul_f32_e32 v140, v164, v204
	v_mul_f32_e32 v141, v165, v205
	v_mul_f32_e32 v142, v166, v206
	v_mul_f32_e32 v143, v167, v207
	v_mul_f32_e32 v144, v168, v208
	v_mul_f32_e32 v145, v169, v209
	v_mul_f32_e32 v146, v170, v210
	v_mul_f32_e32 v147, v171, v211
	v_fmac_f32_e32 v140, v172, v196
	v_fmac_f32_e32 v141, v173, v197
	v_fmac_f32_e32 v142, v174, v198
	v_fmac_f32_e32 v143, v175, v199
	v_fmac_f32_e32 v144, v176, v200
	v_fmac_f32_e32 v145, v177, v201
	v_fmac_f32_e32 v146, v178, v202
	v_fmac_f32_e32 v147, v179, v203
	v_fmac_f32_e32 v140, v180, v188
	v_fmac_f32_e32 v141, v181, v189
	v_fmac_f32_e32 v142, v182, v190
	v_fmac_f32_e32 v143, v183, v191
	v_fmac_f32_e32 v144, v184, v192
	v_fmac_f32_e32 v145, v185, v193
	v_fmac_f32_e32 v146, v186, v194
	v_fmac_f32_e32 v147, v187, v195
	v_lshlrev_b32_e32 v150, 16, v10
	v_and_b32_e32 v151, 0xffff0000, v10
	v_mul_f32_e32 v140, v150, v140
	v_mul_f32_e32 v141, v151, v141
	v_lshlrev_b32_e32 v150, 16, v11
	v_and_b32_e32 v151, 0xffff0000, v11
	v_mul_f32_e32 v142, v150, v142
	v_mul_f32_e32 v143, v151, v143
	v_lshlrev_b32_e32 v150, 16, v12
	v_and_b32_e32 v151, 0xffff0000, v12
	v_mul_f32_e32 v144, v150, v144
	v_mul_f32_e32 v145, v151, v145
	v_lshlrev_b32_e32 v150, 16, v13
	v_and_b32_e32 v151, 0xffff0000, v13
	v_mul_f32_e32 v146, v150, v146
	v_mul_f32_e32 v147, v151, v147
	v_mul_f32_e32 v148, v140, v140
	v_fmac_f32_e32 v148, v141, v141
	v_fmac_f32_e32 v148, v142, v142
	v_fmac_f32_e32 v148, v143, v143
	v_fmac_f32_e32 v148, v144, v144
	v_fmac_f32_e32 v148, v145, v145
	v_fmac_f32_e32 v148, v146, v146
	v_fmac_f32_e32 v148, v147, v147
	s_nop 1
	v_add_f32_dpp v148, v148, v148 quad_perm:[1,0,3,2] row_mask:0xf bank_mask:0xf
	s_nop 1
	v_add_f32_dpp v148, v148, v148 quad_perm:[2,3,0,1] row_mask:0xf bank_mask:0xf
	s_nop 1
	v_add_f32_dpp v148, v148, v148 row_half_mirror row_mask:0xf bank_mask:0xf
	s_nop 1
	v_add_f32_dpp v148, v148, v148 row_mirror row_mask:0xf bank_mask:0xf
	s_nop 1
	v_add_f32_dpp v148, v148, v148 row_bcast:15 row_mask:0xa bank_mask:0xf
	s_nop 1
	v_add_f32_dpp v148, v148, v148 row_bcast:31 row_mask:0xc bank_mask:0xf
	s_nop 0
	v_readlane_b32 s0, v148, 63
	s_nop 1
	v_mov_b32_e32 v148, s0
	v_fmamk_f32 v148, v148, 0x3b000000, v162
	v_mul_f32_e32 v150, 0x4b800000, v148
	v_cmp_gt_f32_e32 vcc, s31, v148
	s_nop 1
	v_cndmask_b32_e32 v148, v148, v150, vcc
	v_rsq_f32_e32 v148, v148
	s_nop 0
	v_mul_f32_e32 v150, 0x45800000, v148
	v_cndmask_b32_e32 v149, v148, v150, vcc
	v_mul_f32_e32 v140, v149, v140
	v_mul_f32_e32 v141, v149, v141
	v_mul_f32_e32 v142, v149, v142
	v_mul_f32_e32 v143, v149, v143
	v_mul_f32_e32 v144, v149, v144
	v_mul_f32_e32 v145, v149, v145
	v_mul_f32_e32 v146, v149, v146
	v_mul_f32_e32 v147, v149, v147
	v_cvt_pk_bf16_f32 v140, v140, v141
	v_cvt_pk_bf16_f32 v141, v142, v143
	v_cvt_pk_bf16_f32 v142, v144, v145
	v_cvt_pk_bf16_f32 v143, v146, v147
	global_store_dwordx4 v[156:157], v[140:143], off
	s_waitcnt vmcnt(4)
; __device__ __forceinline__ unsigned cvt_pk_bf16(float lo, float hi) { unsigned r; asm volatile("v_cvt_pk_bf16_f32 %0, %1, %2" : "=v"(r) : "v"(lo), "v"(hi)); return r; }
; __device__ __forceinline__ float bf_lo(unsigned w) { return __uint_as_float(w << 16); }
; __device__ __forceinline__ float bf_hi(unsigned w) { return __uint_as_float(w & 0xffff0000u); }
; __global__ void __launch_bounds__(512, 2) trunk_fwd(Args args) {
;     ...
;                 for (int rr = 0; rr < 16; ++rr) {
;                     const int r = r0 + rr;
;                     const u32x4 gb = gb_n, gu = gu_n; const f32x4 pv4 = pv_n;
;                     if (rr < 15) { gb_n = *(const u32x4*)(Z + (size_t)(r + 1) * INP + 768 + c0); gu_n = *(const u32x4*)(Z + (size_t)(r + 1) * INP + 1280 + c0);
;                                    pv_n = *(const f32x4*)(pl + (size_t)(r + 1) * PLE + lane * 4); }
;                     float cv[8], uu[8]; float ss = 0.f;
; #pragma unroll
;                     for (int i = 0; i < 4; ++i) {
;                         uu[2 * i] = bf_lo(gu[i]); uu[2 * i + 1] = bf_hi(gu[i]);
;                         cv[2 * i] = bf_lo(gb[i]) * (w0[2 * i] * uu[2 * i] + w1[2 * i] * u1[2 * i] + w2[2 * i] * u2[2 * i]);
;                         cv[2 * i + 1] = bf_hi(gb[i]) * (w0[2 * i + 1] * uu[2 * i + 1] + w1[2 * i + 1] * u1[2 * i + 1] + w2[2 * i + 1] * u2[2 * i + 1]);
;                     }
; #pragma unroll
;                     for (int i = 0; i < 8; ++i) { ss += cv[i] * cv[i]; u2[i] = u1[i]; u1[i] = uu[i]; }
;                     ss = wave_sum(ss);
;                     const float rc = rsqrtf(ss * (1.0f / 512.0f) + EPS);
;                     u32x4 oc;
; #pragma unroll
;                     for (int i = 0; i < 4; ++i) oc[i] = cvt_pk_bf16(cv[2 * i] * rc, cv[2 * i + 1] * rc);
;                     *(u32x4*)(MIX + (size_t)r * 1024 + 512 + c0) = oc;
	v_lshlrev_b32_e32 v188, 16, v30
	v_and_b32_e32 v189, 0xffff0000, v30
	v_lshlrev_b32_e32 v190, 16, v31
	v_and_b32_e32 v191, 0xffff0000, v31
	v_lshlrev_b32_e32 v192, 16, v32
	v_and_b32_e32 v193, 0xffff0000, v32
	v_lshlrev_b32_e32 v194, 16, v33
	v_and_b32_e32 v195, 0xffff0000, v33
	v_mul_f32_e32 v140, v164, v188
	v_mul_f32_e32 v141, v165, v189
	v_mul_f32_e32 v142, v166, v190
	v_mul_f32_e32 v143, v167, v191
	v_mul_f32_e32 v144, v168, v192
	v_mul_f32_e32 v145, v169, v193
	v_mul_f32_e32 v146, v170, v194
	v_mul_f32_e32 v147, v171, v195
	v_fmac_f32_e32 v140, v172, v204
	v_fmac_f32_e32 v141, v173, v205
	v_fmac_f32_e32 v142, v174, v206
	v_fmac_f32_e32 v143, v175, v207
	v_fmac_f32_e32 v144, v176, v208
	v_fmac_f32_e32 v145, v177, v209
	v_fmac_f32_e32 v146, v178, v210
	v_fmac_f32_e32 v147, v179, v211
	v_fmac_f32_e32 v140, v180, v196
	v_fmac_f32_e32 v141, v181, v197
	v_fmac_f32_e32 v142, v182, v198
	v_fmac_f32_e32 v143, v183, v199
	v_fmac_f32_e32 v144, v184, v200
	v_fmac_f32_e32 v145, v185, v201
	v_fmac_f32_e32 v146, v186, v202
	v_fmac_f32_e32 v147, v187, v203
	v_lshlrev_b32_e32 v150, 16, v14
	v_and_b32_e32 v151, 0xffff0000, v14
	v_mul_f32_e32 v140, v150, v140
	v_mul_f32_e32 v141, v151, v141
	v_lshlrev_b32_e32 v150, 16, v15
	v_and_b32_e32 v151, 0xffff0000, v15
	v_mul_f32_e32 v142, v150, v142
	v_mul_f32_e32 v143, v151, v143
	v_lshlrev_b32_e32 v150, 16, v16
	v_and_b32_e32 v151, 0xffff0000, v16
	v_mul_f32_e32 v144, v150, v144
	v_mul_f32_e32 v145, v151, v145
	v_lshlrev_b32_e32 v150, 16, v17
	v_and_b32_e32 v151, 0xffff0000, v17
	v_mul_f32_e32 v146, v150, v146
	v_mul_f32_e32 v147, v151, v147
	v_mul_f32_e32 v148, v140, v140
	v_fmac_f32_e32 v148, v141, v141
	v_fmac_f32_e32 v148, v142, v142
	v_fmac_f32_e32 v148, v143, v143
	v_fmac_f32_e32 v148, v144, v144
	v_fmac_f32_e32 v148, v145, v145
	v_fmac_f32_e32 v148, v146, v146
	v_fmac_f32_e32 v148, v147, v147
	s_nop 1
	v_add_f32_dpp v148, v148, v148 quad_perm:[1,0,3,2] row_mask:0xf bank_mask:0xf
	s_nop 1
	v_add_f32_dpp v148, v148, v148 quad_perm:[2,3,0,1] row_mask:0xf bank_mask:0xf
	s_nop 1
	v_add_f32_dpp v148, v148, v148 row_half_mirror row_mask:0xf bank_mask:0xf
	s_nop 1
	v_add_f32_dpp v148, v148, v148 row_mirror row_mask:0xf bank_mask:0xf
	s_nop 1
	v_add_f32_dpp v148, v148, v148 row_bcast:15 row_mask:0xa bank_mask:0xf
	s_nop 1
	v_add_f32_dpp v148, v148, v148 row_bcast:31 row_mask:0xc bank_mask:0xf
	s_nop 0
	v_readlane_b32 s0, v148, 63
	s_nop 1
	v_mov_b32_e32 v148, s0
	v_fmamk_f32 v148, v148, 0x3b000000, v162
	v_mul_f32_e32 v150, 0x4b800000, v148
	v_cmp_gt_f32_e32 vcc, s31, v148
	s_nop 1
	v_cndmask_b32_e32 v148, v148, v150, vcc
	v_rsq_f32_e32 v148, v148
	s_nop 0
	v_mul_f32_e32 v150, 0x45800000, v148
	v_cndmask_b32_e32 v149, v148, v150, vcc
	v_mul_f32_e32 v140, v149, v140
	v_mul_f32_e32 v141, v149, v141
	v_mul_f32_e32 v142, v149, v142
	v_mul_f32_e32 v143, v149, v143
	v_mul_f32_e32 v144, v149, v144
	v_mul_f32_e32 v145, v149, v145
	v_mul_f32_e32 v146, v149, v146
	v_mul_f32_e32 v147, v149, v147
	v_cvt_pk_bf16_f32 v140, v140, v141
	v_cvt_pk_bf16_f32 v141, v142, v143
	v_cvt_pk_bf16_f32 v142, v144, v145
	v_cvt_pk_bf16_f32 v143, v146, v147
	global_store_dwordx4 v[156:157], v[140:143], off offset:2048
	v_lshl_add_u64 v[156:157], v[156:157], 0, s[20:21]
	s_branch .LBB0_1053
